# gate GEMM unit order: head fixed per workgroup (A tile reused in consecutive steps)
# speedup vs baseline: 1.0099x; 1.0069x over previous
; #define LAS __attribute__((address_space(3)))
; #define PG8_BAR __builtin_amdgcn_s_barrier()
;     __device__ bool next(int i, Unit& u) const {
;         if (sticky) { u.pn = c % nN; u.pm = c / nN + i * (G / nN); return u.pm < nM; }
;         const long L = (long)i * G + c; if (L >= nwg) return false;
;         int wgid = (int)L; { const int q = nwg / NXCD, r = nwg % NXCD, xcd = wgid % NXCD, off = wgid / NXCD; wgid = (xcd < r ? xcd * (q + 1) : r * (q + 1) + (xcd - r) * q) + off; }
;         const int nig = WGM * nN, gid = wgid / nig, fm = gid * WGM, gsz = (nM - fm) < WGM ? (nM - fm) : WGM;
;         u.pm = fm + ((wgid % nig) % gsz); u.pn = (wgid % nig) / gsz; return true;
;     }
; template <class Epi>
; __device__ __forceinline__ void gemm_phase(LAS unsigned char* lds, const Gemm g, const StaticOrder& S_in, const Epi& E, int sw) {
;     StaticOrder S = S_in; asm volatile("" : "+s"(S.c), "+s"(S.G));
;     const int tid = ltid(sw);
;     const int wid = __builtin_amdgcn_readfirstlane(tid >> 6), lane = tid & 63, wr = wid >> 2, wc = wid & 3, fr = lane & 15, fq = lane >> 4;
;     const int K = g.K, nt = K / BK;
;     unsigned voffA[2], voffB[2];
; #pragma unroll
;     for (int i = 0; i < 2; ++i) { int R, C; stage_rc(tid * 16 + i * 8192, R, C); const int Rb = (R & ~31) + perm32(R & 31);
;         voffA[i] = (unsigned)(R * g.lda + C) * 2u; voffB[i] = (unsigned)(Rb * g.ldb + C) * 2u; }
;     const size_t kstep = (size_t)(BK * 2);
;     const size_t hstepA = (size_t)HALF * g.lda * 2, hstepB = (size_t)HALF * g.ldb * 2;
;     const unsigned ldsw = (unsigned)wid * 1024u;
;     const int aoff = lds_byte(wr * 64 + fr, fq * 8), boff = lds_byte(wc * 32 + fr, fq * 8);
;     ...
;     Unit cur, nxt; int ui = 0;
;     if (!S.next(0, cur)) return;
;     f32x4 acc[2][2][4][2];
;     E.init(acc, cur, sw);
;     bf16x8 At[4][2], B0[2][2], B1[2][2];
;     const char* cA = PG8_ABASE(cur); const char* cB = PG8_BBASE(cur);
;     PG8_STAGE(PG8_SB(0, 0), cB, voffB); PG8_STAGE(PG8_SA(0, 0), cA, voffA); PG8_STAGE(PG8_SB(0, 1), cB + hstepB, voffB); PG8_STAGE(PG8_SA(0, 1), cA + hstepA, voffA);
;     if (wr == 1) PG8_BAR;
;     __device__ __forceinline__ void init(AccMut acc, const Unit& u, int sw) const {
;         const int tid_ = ltid(sw), lane_ = tid_ & 63, wc = sw & 3, fq = lane_ >> 4;
;         const int c0 = u.pn * 128 + wc * 32 + 8 * fq;
; #pragma unroll
.LBB0_419:
	s_or_b64 exec, exec, s[8:9]
	s_mov_b64 s[8:9], s[92:93]
	s_waitcnt lgkmcnt(0)
	s_barrier
	s_load_dwordx2 s[12:13], s[8:9], 0xa8
	s_mov_b64 s[8:9], s[92:93]
	s_mov_b64 s[10:11], s[92:93]
	s_load_dwordx2 s[8:9], s[8:9], 0xa8
	s_load_dwordx2 s[10:11], s[10:11], 0xa8
	s_mov_b32 s16, s75
	s_mov_b32 s17, s81
	s_lshl_b32 s80, s36, 4
	v_mbcnt_lo_u32_b32 v0, -1, s17
	v_mbcnt_hi_u32_b32 v0, -1, v0
	v_lshl_add_u32 v26, s16, 6, v0
	s_cmp_lt_i32 s20, s80
	s_cselect_b64 s[16:17], -1, 0
	s_cmp_ge_i32 s20, s80
	v_readfirstlane_b32 s37, v26
	s_cbranch_scc1 .LBB0_421
	s_ashr_i32 s18, s20, 31
	s_lshr_b32 s18, s18, 29
	s_add_i32 s18, s20, s18
	s_ashr_i32 s19, s18, 3
	s_and_b32 s18, s18, -8
	s_sub_i32 s18, s20, s18
	v_mov_b32_e32 v0, s18
	v_alignbit_b32 v0, s36, v0, 31
	s_nop 0
	v_readfirstlane_b32 s21, v0
	s_mul_i32 s18, s21, s18
	s_add_i32 s18, s18, s19
	s_ashr_i32 s19, s18, 31
	s_lshr_b32 s19, s19, 25
	s_add_i32 s19, s18, s19
	s_ashr_i32 s21, s19, 7
	s_lshl_b32 s21, s21, 3
	s_sub_i32 s22, s36, s21
	s_min_i32 s23, s22, 8
	s_abs_i32 s22, s23
	v_cvt_f32_u32_e32 v0, s22
	s_sub_i32 s25, 0, s22
	s_and_b32 s19, s19, 0xffffff80
	s_sub_i32 s18, s18, s19
	v_rcp_iflag_f32_e32 v0, v0
	s_abs_i32 s19, s18
	s_xor_b32 s24, s18, s23
	s_ashr_i32 s24, s24, 31
	v_mul_f32_e32 v0, 0x4f7ffffe, v0
	v_cvt_u32_f32_e32 v0, v0
	s_nop 0
	v_readfirstlane_b32 s26, v0
	s_mul_i32 s25, s25, s26
	s_mul_hi_u32 s25, s26, s25
	s_add_i32 s26, s26, s25
	s_mul_hi_u32 s25, s19, s26
	s_mul_i32 s26, s25, s22
	s_sub_i32 s19, s19, s26
	s_add_i32 s27, s25, 1
	s_sub_i32 s26, s19, s22
	s_cmp_ge_u32 s19, s22
	s_cselect_b32 s25, s27, s25
	s_cselect_b32 s19, s26, s19
	s_add_i32 s26, s25, 1
	s_cmp_ge_u32 s19, s22
	s_cselect_b32 s19, s26, s25
	s_xor_b32 s19, s19, s24
	s_sub_i32 s22, s19, s24
	s_mul_i32 s19, s22, s23
	s_sub_i32 s18, s18, s19
	s_add_i32 s24, s18, s21
	s_cmp_lg_u32 s15, 32
	s_cbranch_scc1 .Lgate_ord0_keep
	s_cmp_lg_u32 s36, 16
	s_cbranch_scc1 .Lgate_ord0_keep
	s_lshr_b32 s24, s20, 3
	s_lshl_b32 s24, s24, 2
	s_and_b32 s22, s20, 7
	s_lshl_b32 s22, s22, 1
.Lgate_ord0_keep:
.LBB0_421:
	s_andn2_b64 vcc, exec, s[16:17]
	s_cbranch_vccnz .LBB0_497
	v_bfe_i32 v3, v26, 27, 1
	v_lshlrev_b32_e32 v2, 4, v26
	v_lshrrev_b32_e32 v3, 22, v3
	v_add_u32_e32 v3, v2, v3
	v_and_b32_e32 v3, 0xfffffc00, v3
	v_sub_u32_e32 v3, v2, v3
	v_ashrrev_i32_e32 v0, 31, v26
	v_lshrrev_b32_e32 v4, 4, v3
	v_lshrrev_b32_e32 v0, 26, v0
	v_bitop3_b32 v4, v4, v3, 32 bitop3:0x6c
	v_ashrrev_i32_e32 v3, 31, v3
	v_add_u32_e32 v0, v26, v0
	v_lshrrev_b32_e32 v3, 26, v3
	v_ashrrev_i32_e32 v0, 6, v0
	v_add_u32_e32 v3, v4, v3
	v_lshlrev_b32_e32 v5, 3, v0
	v_ashrrev_i32_e32 v3, 6, v3
	v_and_b32_e32 v5, -16, v5
	v_mul_i32_i24_e32 v6, 64, v3
	v_add_u32_e32 v5, v3, v5
	v_sub_u32_e32 v4, v4, v6
	v_lshlrev_b32_e32 v0, 5, v0
	v_ashrrev_i16_sdwa v4, v244, sext(v4) dst_sel:DWORD dst_unused:UNUSED_PAD src0_sel:DWORD src1_sel:BYTE_0
	v_lshlrev_b32_e32 v6, 1, v5
	v_lshrrev_b32_e32 v7, 2, v5
	v_and_b32_e32 v3, 3, v3
	s_mov_b32 s17, 0x7fffe0
	v_and_b32_e32 v0, 32, v0
	v_bfe_i32 v4, v4, 0, 16
	v_and_b32_e32 v6, 24, v6
	v_and_b32_e32 v7, 4, v7
	v_and_or_b32 v3, v5, s17, v3
	v_or3_b32 v3, v3, v7, v6
	v_add_lshl_u32 v0, v0, v4, 1
	v_add_u32_e32 v2, 0x2000, v2
	v_lshl_add_u32 v130, v5, 12, v0
	v_lshl_add_u32 v0, v3, 9, v0
	v_ashrrev_i32_e32 v3, 31, v2
	v_lshrrev_b32_e32 v3, 22, v3
	v_add_u32_e32 v3, v2, v3
	v_ashrrev_i32_e32 v3, 10, v3
	v_mul_i32_i24_e32 v4, 0x400, v3
	v_sub_u32_e32 v2, v2, v4
	v_lshrrev_b32_e32 v4, 4, v2
	v_bitop3_b32 v2, v4, v2, 32 bitop3:0x6c
	v_ashrrev_i32_e32 v5, 31, v2
	v_lshrrev_b32_e32 v5, 26, v5
	v_lshlrev_b32_e32 v4, 3, v3
	v_add_u32_e32 v5, v2, v5
	v_and_b32_e32 v4, -16, v4
	v_ashrrev_i32_e32 v6, 6, v5
	v_add_u32_e32 v4, v6, v4
	v_and_b32_e32 v6, 3, v6
	v_and_or_b32 v6, v4, s17, v6
	s_ashr_i32 s17, s37, 6
	s_ashr_i32 s16, s37, 8
	s_lshl_b32 s38, s17, 10
	s_lshl_b64 s[0:1], s[0:1], 1
	s_add_u32 s6, s6, s0
	v_and_b32_e32 v5, 0xc0, v5
	s_addc_u32 s7, s7, s1
	v_sub_u32_e32 v2, v2, v5
	s_add_u32 s39, s6, 0xe000000
	v_lshlrev_b32_e32 v3, 5, v3
	v_ashrrev_i16_sdwa v2, v244, sext(v2) dst_sel:DWORD dst_unused:UNUSED_PAD src0_sel:DWORD src1_sel:BYTE_0
	v_lshlrev_b32_e32 v5, 1, v4
	v_lshrrev_b32_e32 v7, 2, v4
	s_addc_u32 s40, s7, 0
	v_and_b32_e32 v3, 32, v3
	v_bfe_i32 v2, v2, 0, 16
	v_and_b32_e32 v5, 24, v5
	v_and_b32_e32 v7, 4, v7
	s_add_u32 s41, s4, 0x1e800000
	v_or3_b32 v5, v6, v7, v5
	v_add_lshl_u32 v2, v3, v2, 1
	s_addc_u32 s42, s5, 0
	s_mov_b32 s4, s75
	s_mov_b32 s5, s81
	v_lshl_add_u32 v132, v4, 12, v2
	v_lshl_add_u32 v134, v5, 9, v2
	s_ashr_i32 s25, s24, 31
	v_mbcnt_lo_u32_b32 v2, -1, s5
	v_mbcnt_hi_u32_b32 v2, -1, v2
	v_lshl_add_u32 v2, s4, 6, v2
	s_lshl_b32 s4, s22, 7
	v_lshrrev_b32_e32 v2, 1, v2
	v_and_or_b32 v2, v2, 24, s4
	s_ashr_i32 s4, s22, 1
	s_ashr_i32 s5, s4, 31
	s_lshl_b64 s[6:7], s[24:25], 20
	s_add_u32 s18, s39, s6
	s_addc_u32 s19, s40, s7
	s_ashr_i32 s23, s22, 31
	s_lshl_b64 s[6:7], s[22:23], 17
	v_or_b32_e32 v2, s85, v2
	s_add_u32 s28, s41, s6
	v_lshl_add_u32 v2, v2, 2, 0
	s_addc_u32 s29, s42, s7
	s_add_i32 s23, s38, 0
	v_add_u32_e32 v3, 0x20400, v2
	v_add_u32_e32 v6, 0x22400, v2
	s_add_i32 m0, s23, 0x10000
	ds_read_b128 v[10:13], v3
	ds_read_b128 v[14:17], v3 offset:16
	ds_read_b128 v[2:5], v6
	ds_read_b128 v[6:9], v6 offset:16
	global_load_lds_dwordx4 v0, s[28:29]
	s_add_i32 m0, s23, 0x12000
	s_lshl_b64 s[4:5], s[4:5], 9
	s_add_u32 s26, s18, s4
	global_load_lds_dwordx4 v134, s[28:29]
	s_addc_u32 s27, s19, s5
	s_mov_b32 m0, s23
	s_add_i32 s25, s23, 0x2000
	global_load_lds_dwordx4 v130, s[26:27]
	s_mov_b32 m0, s25
	s_add_u32 s4, s28, 0x10000
	global_load_lds_dwordx4 v132, s[26:27]
	s_addc_u32 s5, s29, 0
	s_add_i32 m0, s23, 0x14000
	v_mov_b32_e32 v135, v1
	global_load_lds_dwordx4 v0, s[4:5]
	s_add_i32 m0, s23, 0x16000
	v_mov_b32_e32 v131, v1
	global_load_lds_dwordx4 v134, s[4:5]
	s_add_u32 s4, s26, 0x80000
	s_addc_u32 s5, s27, 0
	s_add_i32 s43, s23, 0x4000
	s_mov_b32 m0, s43
	s_add_i32 s44, s23, 0x6000
	global_load_lds_dwordx4 v130, s[4:5]
	s_mov_b32 m0, s44
	v_mov_b32_e32 v133, v1
	global_load_lds_dwordx4 v132, s[4:5]
	v_lshl_add_u64 v[24:25], s[28:29], 0, v[0:1]
	v_lshl_add_u64 v[22:23], s[28:29], 0, v[134:135]
	v_lshl_add_u64 v[20:21], s[26:27], 0, v[130:131]
	s_cmp_lg_u32 s16, 1
	v_lshl_add_u64 v[18:19], s[26:27], 0, v[132:133]
	s_cbranch_scc1 .LBB0_424
	s_barrier

; #define PG8_STAGE(bufoff, gbase, voff) do { _Pragma("unroll") for (int _i = 0; _i < 2; ++_i) \
;         __builtin_amdgcn_global_load_lds((const __attribute__((address_space(1))) unsigned*)((const char*)(gbase) + (voff)[_i]), (LAS unsigned*)(lds + (bufoff) + ldsw + _i * 8192), 16, 0, 0); } while (0)
; #define PG8_LDA(dst, b, h) do { _Pragma("unroll") for (int m = 0; m < 4; ++m) _Pragma("unroll") for (int k = 0; k < 2; ++k) dst[m][k] = *(const LAS bf16x8*)(lds + PG8_SA(b, h) + aoff + m * 2048 + k * 1024); } while (0)
; #define PG8_WAIT_L(n) asm volatile("s_waitcnt lgkmcnt(" #n ")" ::: "memory")
;     __device__ bool next(int i, Unit& u) const {
;         if (sticky) { u.pn = c % nN; u.pm = c / nN + i * (G / nN); return u.pm < nM; }
;         const long L = (long)i * G + c; if (L >= nwg) return false;
;         int wgid = (int)L; { const int q = nwg / NXCD, r = nwg % NXCD, xcd = wgid % NXCD, off = wgid / NXCD; wgid = (xcd < r ? xcd * (q + 1) : r * (q + 1) + (xcd - r) * q) + off; }
;         const int nig = WGM * nN, gid = wgid / nig, fm = gid * WGM, gsz = (nM - fm) < WGM ? (nM - fm) : WGM;
;         u.pm = fm + ((wgid % nig) % gsz); u.pn = (wgid % nig) / gsz; return true;
; template <class Epi>
; __device__ __forceinline__ void gemm_phase(LAS unsigned char* lds, const Gemm g, const StaticOrder& S_in, const Epi& E, int sw) {
;     ...
;         const bool has_next = S.next(ui + 1, nxt);
;         const char* nA = has_next ? PG8_ABASE(nxt) : cA; const char* nB = has_next ? PG8_BBASE(nxt) : cB;
;         for (int t = 0; t < nt; t += 2) {
;             const bool last = (t == nt - 2);
;             const char* a1 = cA + (size_t)(t + 1) * kstep;
;             const char* a2 = last ? nA : cA + (size_t)(t + 2) * kstep; const char* b2 = last ? nB : cB + (size_t)(t + 2) * kstep;
;             const char* a3 = a2 + kstep; const char* b3 = b2 + kstep;
;             PG8_LDB(B0, 0, 0); PG8_SCHED; PG8_LDA(At, 0, 0); PG8_STAGE(PG8_SA(1, 1), a1 + hstepA, voffA);
;             PG8_WAIT_L(8); PG8_BAR; PG8_WAIT_L(0); PG8_MMA(0, 0, At, B0); PG8_BAR; PG8_SCHED;
;             PG8_LDB(B1, 0, 1); PG8_STAGE(PG8_SB(0, 0), b2, voffB);
;             PG8_BAR; PG8_WAIT_L(0); PG8_MMA(0, 1, At, B1); PG8_BAR;
;             PG8_LDA(At, 0, 1); PG8_STAGE(PG8_SA(0, 0), a2, voffA);
;             PG8_BAR; PG8_WAIT_L(0); PG8_MMA(1, 0, At, B0); PG8_BAR; PG8_SCHED;
.LBB0_426:
	v_mov_b64_e32 v[18:19], s[80:81]
	v_cmp_ge_i64_e32 vcc, s[0:1], v[18:19]
	v_cmp_lt_i64_e64 s[4:5], s[0:1], v[18:19]
	s_cbranch_vccnz .LBB0_428
	s_ashr_i32 s12, s0, 31
	s_lshr_b32 s12, s12, 29
	s_add_i32 s12, s0, s12
	s_ashr_i32 s13, s12, 3
	s_and_b32 s12, s12, -8
	s_sub_i32 s12, s0, s12
	v_mov_b32_e32 v18, s12
	v_alignbit_b32 v18, s36, v18, 31
	s_nop 0
	v_readfirstlane_b32 s16, v18
	s_mul_i32 s12, s16, s12
	s_add_i32 s12, s12, s13
	s_ashr_i32 s13, s12, 31
	s_lshr_b32 s13, s13, 25
	s_add_i32 s13, s12, s13
	s_ashr_i32 s16, s13, 7
	s_lshl_b32 s16, s16, 3
	s_sub_i32 s17, s36, s16
	s_min_i32 s17, s17, 8
	s_abs_i32 s18, s17
	v_cvt_f32_u32_e32 v18, s18
	s_sub_i32 s20, 0, s18
	s_and_b32 s13, s13, 0xffffff80
	s_sub_i32 s13, s12, s13
	v_rcp_iflag_f32_e32 v18, v18
	s_abs_i32 s12, s13
	s_xor_b32 s19, s13, s17
	s_ashr_i32 s19, s19, 31
	v_mul_f32_e32 v18, 0x4f7ffffe, v18
	v_cvt_u32_f32_e32 v18, v18
	s_nop 0
	v_readfirstlane_b32 s21, v18
	s_mul_i32 s20, s20, s21
	s_mul_hi_u32 s20, s21, s20
	s_add_i32 s21, s21, s20
	s_mul_hi_u32 s20, s12, s21
	s_mul_i32 s21, s20, s18
	s_sub_i32 s12, s12, s21
	s_add_i32 s30, s20, 1
	s_sub_i32 s21, s12, s18
	s_cmp_ge_u32 s12, s18
	s_cselect_b32 s20, s30, s20
	s_cselect_b32 s12, s21, s12
	s_add_i32 s21, s20, 1
	s_cmp_ge_u32 s12, s18
	s_cselect_b32 s12, s21, s20
	s_xor_b32 s12, s12, s19
	s_sub_i32 s12, s12, s19
	s_mul_i32 s17, s12, s17
	s_sub_i32 s13, s13, s17
	s_add_i32 s16, s13, s16
	s_cmp_lg_u32 s15, 32
	s_cbranch_scc1 .Lgate_ord_keep
	s_cmp_lg_u32 s36, 16
	s_cbranch_scc1 .Lgate_ord_keep
	s_bfe_u32 s16, s0, 0x20003
	s_lshl_b32 s16, s16, 2
	s_lshr_b32 s13, s0, 6
	s_or_b32 s16, s16, s13
	s_and_b32 s12, s0, 7
	s_lshl_b32 s12, s12, 1
	s_bfe_u32 s13, s0, 0x10005
	s_or_b32 s12, s12, s13
.Lgate_ord_keep:
.LBB0_428:
	s_ashr_i32 s18, s12, 1
	s_ashr_i32 s17, s16, 31
	s_ashr_i32 s19, s18, 31
	s_lshl_b64 s[18:19], s[18:19], 9
	s_lshl_b64 s[20:21], s[16:17], 20
	s_add_u32 s13, s39, s20
	s_addc_u32 s17, s40, s21
	s_add_u32 s18, s13, s18
	s_addc_u32 s19, s17, s19
	s_and_b64 s[20:21], s[4:5], exec
	s_cselect_b32 s35, s19, s27
	s_cselect_b32 s34, s18, s26
	s_ashr_i32 s13, s12, 31
	s_lshl_b64 s[20:21], s[12:13], 17
	s_add_u32 s20, s41, s20
	s_addc_u32 s21, s42, s21
	s_and_b64 s[30:31], s[4:5], exec
	s_cselect_b32 s31, s21, s29
	s_cselect_b32 s30, s20, s28
	s_add_i32 s17, 0, 0x10000
	v_add_u32_e32 v175, s17, v171
	ds_read_b128 v[18:21], v175
	ds_read_b128 v[22:25], v175 offset:1024
	ds_read_b128 v[26:29], v175 offset:2048
	ds_read_b128 v[30:33], v175 offset:3072
	s_add_u32 s48, s26, 0x80080
	s_addc_u32 s49, s27, 0
	s_add_i32 s50, s23, 0xc000
	v_lshl_add_u64 v[66:67], s[48:49], 0, v[130:131]
	s_mov_b32 m0, s50
	s_add_i32 s13, s23, 0xe000
	ds_read_b128 v[34:37], v174
	ds_read_b128 v[38:41], v174 offset:1024
	ds_read_b128 v[42:45], v174 offset:2048
	ds_read_b128 v[46:49], v174 offset:3072
	ds_read_b128 v[50:53], v174 offset:4096
	ds_read_b128 v[54:57], v174 offset:5120
	ds_read_b128 v[58:61], v174 offset:6144
	ds_read_b128 v[62:65], v174 offset:7168
	global_load_lds_dwordx4 v[66:67], off
	v_lshl_add_u64 v[66:67], s[48:49], 0, v[132:133]
	s_mov_b32 m0, s13
	s_nop 0
	global_load_lds_dwordx4 v[66:67], off
	s_waitcnt lgkmcnt(8)
	s_barrier
	s_waitcnt lgkmcnt(0)
	s_setprio 1
	s_waitcnt lgkmcnt(0)
	v_mfma_f32_16x16x32_bf16 v[66:69], v[18:21], v[34:37], v[10:13]
	v_mfma_f32_16x16x32_bf16 v[70:73], v[26:29], v[34:37], v[14:17]
	v_mfma_f32_16x16x32_bf16 v[74:77], v[18:21], v[42:45], v[10:13]
	v_mfma_f32_16x16x32_bf16 v[78:81], v[26:29], v[42:45], v[14:17]
	v_mfma_f32_16x16x32_bf16 v[82:85], v[18:21], v[50:53], v[10:13]
	v_mfma_f32_16x16x32_bf16 v[86:89], v[26:29], v[50:53], v[14:17]
	v_mfma_f32_16x16x32_bf16 v[90:93], v[18:21], v[58:61], v[10:13]
	v_mfma_f32_16x16x32_bf16 v[94:97], v[26:29], v[58:61], v[14:17]
	v_mfma_f32_16x16x32_bf16 v[66:69], v[22:25], v[38:41], v[66:69]
	v_mfma_f32_16x16x32_bf16 v[70:73], v[30:33], v[38:41], v[70:73]
	v_mfma_f32_16x16x32_bf16 v[74:77], v[22:25], v[46:49], v[74:77]
	v_mfma_f32_16x16x32_bf16 v[78:81], v[30:33], v[46:49], v[78:81]
	v_mfma_f32_16x16x32_bf16 v[82:85], v[22:25], v[54:57], v[82:85]
	v_mfma_f32_16x16x32_bf16 v[86:89], v[30:33], v[54:57], v[86:89]
	v_mfma_f32_16x16x32_bf16 v[90:93], v[22:25], v[62:65], v[90:93]
	v_mfma_f32_16x16x32_bf16 v[94:97], v[30:33], v[62:65], v[94:97]
	s_setprio 0
	s_barrier
	s_add_i32 s51, 0, 0x14000
	v_lshl_add_u64 v[168:169], s[28:29], 0, v[0:1]
	s_mov_b64 s[52:53], 0x100
	s_add_i32 s49, s17, s38
	v_add_u32_e32 v212, s51, v171
	v_lshl_add_u64 v[114:115], v[168:169], 0, s[52:53]
	s_mov_b32 m0, s49
	v_lshl_add_u64 v[172:173], s[28:29], 0, v[134:135]
	s_add_i32 s17, s49, 0x2000
	ds_read_b128 v[98:101], v212
	ds_read_b128 v[102:105], v212 offset:1024
	ds_read_b128 v[106:109], v212 offset:2048
	ds_read_b128 v[110:113], v212 offset:3072
	global_load_lds_dwordx4 v[114:115], off
	v_lshl_add_u64 v[114:115], v[172:173], 0, s[52:53]
	s_mov_b32 m0, s17
	s_nop 0
	global_load_lds_dwordx4 v[114:115], off
	s_barrier
	s_waitcnt lgkmcnt(0)
	s_setprio 1
	s_waitcnt lgkmcnt(0)
	v_mfma_f32_16x16x32_bf16 v[114:117], v[98:101], v[34:37], v[2:5]
	v_mfma_f32_16x16x32_bf16 v[34:37], v[106:109], v[34:37], v[6:9]
	v_mfma_f32_16x16x32_bf16 v[114:117], v[102:105], v[38:41], v[114:117]
	v_mfma_f32_16x16x32_bf16 v[34:37], v[110:113], v[38:41], v[34:37]
	v_mfma_f32_16x16x32_bf16 v[38:41], v[98:101], v[42:45], v[2:5]
	v_mfma_f32_16x16x32_bf16 v[42:45], v[106:109], v[42:45], v[6:9]
	v_mfma_f32_16x16x32_bf16 v[38:41], v[102:105], v[46:49], v[38:41]
	v_mfma_f32_16x16x32_bf16 v[42:45], v[110:113], v[46:49], v[42:45]
	v_mfma_f32_16x16x32_bf16 v[46:49], v[98:101], v[50:53], v[2:5]
	v_mfma_f32_16x16x32_bf16 v[50:53], v[106:109], v[50:53], v[6:9]
	v_mfma_f32_16x16x32_bf16 v[46:49], v[102:105], v[54:57], v[46:49]
	v_mfma_f32_16x16x32_bf16 v[50:53], v[110:113], v[54:57], v[50:53]
	v_mfma_f32_16x16x32_bf16 v[54:57], v[98:101], v[58:61], v[2:5]
	v_mfma_f32_16x16x32_bf16 v[58:61], v[106:109], v[58:61], v[6:9]
	v_mfma_f32_16x16x32_bf16 v[54:57], v[102:105], v[62:65], v[54:57]
	v_mfma_f32_16x16x32_bf16 v[58:61], v[110:113], v[62:65], v[58:61]
	s_setprio 0
	v_lshl_add_u64 v[208:209], s[26:27], 0, v[130:131]
	s_mov_b32 m0, s23
	v_lshl_add_u64 v[152:153], v[208:209], 0, s[52:53]
	v_lshl_add_u64 v[210:211], s[26:27], 0, v[132:133]
	s_barrier
; #define PG8_STAGE(bufoff, gbase, voff) do { _Pragma("unroll") for (int _i = 0; _i < 2; ++_i) \
;         __builtin_amdgcn_global_load_lds((const __attribute__((address_space(1))) unsigned*)((const char*)(gbase) + (voff)[_i]), (LAS unsigned*)(lds + (bufoff) + ldsw + _i * 8192), 16, 0, 0); } while (0)
; #define PG8_LDA(dst, b, h) do { _Pragma("unroll") for (int m = 0; m < 4; ++m) _Pragma("unroll") for (int k = 0; k < 2; ++k) dst[m][k] = *(const LAS bf16x8*)(lds + PG8_SA(b, h) + aoff + m * 2048 + k * 1024); } while (0)
; #define PG8_LDB(dst, b, h) do { _Pragma("unroll") for (int n = 0; n < 2; ++n) _Pragma("unroll") for (int k = 0; k < 2; ++k) dst[n][k] = *(const LAS bf16x8*)(lds + PG8_SB(b, h) + boff + n * 2048 + k * 1024); } while (0)
; #define PG8_MMA(ai, bj, At, Bt) do { __builtin_amdgcn_s_setprio(1); _Pragma("unroll") for (int m = 0; m < 4; ++m) _Pragma("unroll") for (int n = 0; n < 2; ++n) _Pragma("unroll") for (int k = 0; k < 2; ++k) \
;         acc[ai][bj][m][n] = __builtin_amdgcn_mfma_f32_16x16x32_bf16(Bt[n][k], At[m][k], acc[ai][bj][m][n], 0, 0, 0); __builtin_amdgcn_s_setprio(0); } while (0)
; #define PG8_WAIT_V(n) asm volatile("s_waitcnt vmcnt(" #n ")" ::: "memory")
; #define PG8_WAIT_L(n) asm volatile("s_waitcnt lgkmcnt(" #n ")" ::: "memory")
; #define PG8_BAR __builtin_amdgcn_s_barrier()
; #define PG8_SCHED __builtin_amdgcn_sched_barrier(0)
; template <class Epi>
; __device__ __forceinline__ void gemm_phase(LAS unsigned char* lds, const Gemm g, const StaticOrder& S_in, const Epi& E, int sw) {
;     ...
;             PG8_LDA(At, 0, 1); PG8_STAGE(PG8_SA(0, 0), a2, voffA);
;             PG8_BAR; PG8_WAIT_L(0); PG8_MMA(1, 0, At, B0); PG8_BAR; PG8_SCHED;
;             PG8_STAGE(PG8_SB(0, 1), b2 + hstepB, voffB);
;             PG8_WAIT_V(6); PG8_BAR; PG8_MMA(1, 1, At, B1); PG8_BAR;
;             PG8_LDB(B0, 1, 0); PG8_SCHED; PG8_LDA(At, 1, 0); PG8_STAGE(PG8_SA(0, 1), a2 + hstepA, voffA);
;             PG8_WAIT_L(8); PG8_BAR; PG8_WAIT_L(0); PG8_MMA(0, 0, At, B0); PG8_BAR; PG8_SCHED;
;             PG8_LDB(B1, 1, 1); PG8_STAGE(PG8_SB(1, 0), b3, voffB);
	ds_read_b128 v[62:65], v174 offset:16384
	ds_read_b128 v[118:121], v174 offset:17408
	ds_read_b128 v[122:125], v174 offset:18432
	ds_read_b128 v[126:129], v174 offset:19456
	ds_read_b128 v[136:139], v174 offset:20480
	ds_read_b128 v[140:143], v174 offset:21504
	ds_read_b128 v[144:147], v174 offset:22528
	ds_read_b128 v[148:151], v174 offset:23552
	global_load_lds_dwordx4 v[152:153], off
	v_lshl_add_u64 v[152:153], v[210:211], 0, s[52:53]
	s_mov_b32 m0, s25
	s_nop 0
	global_load_lds_dwordx4 v[152:153], off
	s_barrier
	s_waitcnt lgkmcnt(0)
	s_setprio 1
	s_waitcnt lgkmcnt(0)
	v_mfma_f32_16x16x32_bf16 v[152:155], v[18:21], v[62:65], v[10:13]
	v_mfma_f32_16x16x32_bf16 v[156:159], v[26:29], v[62:65], v[14:17]
	v_mfma_f32_16x16x32_bf16 v[160:163], v[18:21], v[122:125], v[10:13]
	v_mfma_f32_16x16x32_bf16 v[164:167], v[26:29], v[122:125], v[14:17]
	v_mfma_f32_16x16x32_bf16 v[176:179], v[18:21], v[136:139], v[10:13]
	v_mfma_f32_16x16x32_bf16 v[180:183], v[26:29], v[136:139], v[14:17]
	v_mfma_f32_16x16x32_bf16 v[10:13], v[18:21], v[144:147], v[10:13]
	v_mfma_f32_16x16x32_bf16 v[14:17], v[26:29], v[144:147], v[14:17]
	v_mfma_f32_16x16x32_bf16 v[152:155], v[22:25], v[118:121], v[152:155]
	v_mfma_f32_16x16x32_bf16 v[156:159], v[30:33], v[118:121], v[156:159]
	v_mfma_f32_16x16x32_bf16 v[160:163], v[22:25], v[126:129], v[160:163]
	v_mfma_f32_16x16x32_bf16 v[164:167], v[30:33], v[126:129], v[164:167]
	v_mfma_f32_16x16x32_bf16 v[10:13], v[22:25], v[148:151], v[10:13]
	v_mfma_f32_16x16x32_bf16 v[14:17], v[30:33], v[148:151], v[14:17]
	v_mfma_f32_16x16x32_bf16 v[176:179], v[22:25], v[140:143], v[176:179]
	v_mfma_f32_16x16x32_bf16 v[180:183], v[30:33], v[140:143], v[180:183]
	s_setprio 0
	s_barrier
	s_add_u32 s52, s28, 0x10100
	s_addc_u32 s53, s29, 0
	s_add_i32 s51, s51, s38
	v_lshl_add_u64 v[18:19], s[52:53], 0, v[0:1]
	s_mov_b32 m0, s51
	s_add_i32 s48, s51, 0x2000
	global_load_lds_dwordx4 v[18:19], off
	v_lshl_add_u64 v[18:19], s[52:53], 0, v[134:135]
	s_mov_b32 m0, s48
	s_nop 0
	global_load_lds_dwordx4 v[18:19], off
	s_waitcnt vmcnt(6)
	s_barrier
	s_setprio 1
	v_mfma_f32_16x16x32_bf16 v[18:21], v[98:101], v[62:65], v[2:5]
	v_mfma_f32_16x16x32_bf16 v[22:25], v[106:109], v[62:65], v[6:9]
	v_mfma_f32_16x16x32_bf16 v[18:21], v[102:105], v[118:121], v[18:21]
	v_mfma_f32_16x16x32_bf16 v[22:25], v[110:113], v[118:121], v[22:25]
	v_mfma_f32_16x16x32_bf16 v[26:29], v[98:101], v[122:125], v[2:5]
	v_mfma_f32_16x16x32_bf16 v[30:33], v[106:109], v[122:125], v[6:9]
	v_mfma_f32_16x16x32_bf16 v[62:65], v[98:101], v[136:139], v[2:5]
	v_mfma_f32_16x16x32_bf16 v[118:121], v[106:109], v[136:139], v[6:9]
	v_mfma_f32_16x16x32_bf16 v[2:5], v[98:101], v[144:147], v[2:5]
	v_mfma_f32_16x16x32_bf16 v[6:9], v[106:109], v[144:147], v[6:9]
	v_mfma_f32_16x16x32_bf16 v[26:29], v[102:105], v[126:129], v[26:29]
	v_mfma_f32_16x16x32_bf16 v[30:33], v[110:113], v[126:129], v[30:33]
	v_mfma_f32_16x16x32_bf16 v[62:65], v[102:105], v[140:143], v[62:65]
	v_mfma_f32_16x16x32_bf16 v[118:121], v[110:113], v[140:143], v[118:121]
	v_mfma_f32_16x16x32_bf16 v[2:5], v[102:105], v[148:151], v[2:5]
	v_mfma_f32_16x16x32_bf16 v[6:9], v[110:113], v[148:151], v[6:9]
	s_setprio 0
	s_add_i32 s54, 0, 0x18000
	v_add_u32_e32 v220, s54, v171
	s_barrier
	ds_read_b128 v[98:101], v220
	ds_read_b128 v[102:105], v220 offset:1024
	ds_read_b128 v[106:109], v220 offset:2048
	ds_read_b128 v[110:113], v220 offset:3072
	s_add_u32 s52, s26, 0x80100
	s_addc_u32 s53, s27, 0
	s_mov_b32 m0, s43
	v_lshl_add_u64 v[192:193], s[52:53], 0, v[130:131]
	ds_read_b128 v[122:125], v174 offset:32768
	ds_read_b128 v[126:129], v174 offset:33792
	ds_read_b128 v[136:139], v174 offset:34816
	ds_read_b128 v[140:143], v174 offset:35840
	ds_read_b128 v[144:147], v174 offset:36864
	ds_read_b128 v[148:151], v174 offset:37888
	ds_read_b128 v[184:187], v174 offset:38912
	ds_read_b128 v[188:191], v174 offset:39936
	global_load_lds_dwordx4 v[192:193], off
	v_lshl_add_u64 v[192:193], s[52:53], 0, v[132:133]
	s_mov_b32 m0, s44
	s_nop 0
	global_load_lds_dwordx4 v[192:193], off
	s_waitcnt lgkmcnt(8)
	s_barrier
	s_waitcnt lgkmcnt(0)
	s_setprio 1
	s_waitcnt lgkmcnt(0)
	v_mfma_f32_16x16x32_bf16 v[66:69], v[98:101], v[122:125], v[66:69]
	v_mfma_f32_16x16x32_bf16 v[70:73], v[106:109], v[122:125], v[70:73]
	v_mfma_f32_16x16x32_bf16 v[74:77], v[98:101], v[136:139], v[74:77]
	v_mfma_f32_16x16x32_bf16 v[78:81], v[106:109], v[136:139], v[78:81]
	v_mfma_f32_16x16x32_bf16 v[82:85], v[98:101], v[144:147], v[82:85]
	v_mfma_f32_16x16x32_bf16 v[86:89], v[106:109], v[144:147], v[86:89]
	v_mfma_f32_16x16x32_bf16 v[90:93], v[98:101], v[184:187], v[90:93]
	v_mfma_f32_16x16x32_bf16 v[94:97], v[106:109], v[184:187], v[94:97]
	v_mfma_f32_16x16x32_bf16 v[66:69], v[102:105], v[126:129], v[66:69]
	v_mfma_f32_16x16x32_bf16 v[70:73], v[110:113], v[126:129], v[70:73]
	v_mfma_f32_16x16x32_bf16 v[74:77], v[102:105], v[140:143], v[74:77]
	v_mfma_f32_16x16x32_bf16 v[78:81], v[110:113], v[140:143], v[78:81]
	v_mfma_f32_16x16x32_bf16 v[82:85], v[102:105], v[148:151], v[82:85]
	v_mfma_f32_16x16x32_bf16 v[86:89], v[110:113], v[148:151], v[86:89]
	v_mfma_f32_16x16x32_bf16 v[90:93], v[102:105], v[188:191], v[90:93]
	v_mfma_f32_16x16x32_bf16 v[94:97], v[110:113], v[188:191], v[94:97]
	s_setprio 0
	s_barrier
	s_add_i32 s56, 0, 0x1c000
	s_mov_b64 s[58:59], 0x180
	s_add_i32 s53, s54, s38
	v_add_u32_e32 v232, s56, v171
	v_lshl_add_u64 v[168:169], v[168:169], 0, s[58:59]
	s_mov_b32 m0, s53
	s_add_i32 s52, s53, 0x2000
	ds_read_b128 v[192:195], v232
	ds_read_b128 v[196:199], v232 offset:1024
	ds_read_b128 v[200:203], v232 offset:2048
	ds_read_b128 v[204:207], v232 offset:3072
	global_load_lds_dwordx4 v[168:169], off
	v_lshl_add_u64 v[168:169], v[172:173], 0, s[58:59]
	s_mov_b32 m0, s52
	s_nop 0
	global_load_lds_dwordx4 v[168:169], off
	s_barrier
; #define PG8_STAGE(bufoff, gbase, voff) do { _Pragma("unroll") for (int _i = 0; _i < 2; ++_i) \
;         __builtin_amdgcn_global_load_lds((const __attribute__((address_space(1))) unsigned*)((const char*)(gbase) + (voff)[_i]), (LAS unsigned*)(lds + (bufoff) + ldsw + _i * 8192), 16, 0, 0); } while (0)
; #define PG8_LDA(dst, b, h) do { _Pragma("unroll") for (int m = 0; m < 4; ++m) _Pragma("unroll") for (int k = 0; k < 2; ++k) dst[m][k] = *(const LAS bf16x8*)(lds + PG8_SA(b, h) + aoff + m * 2048 + k * 1024); } while (0)
; #define PG8_LDB(dst, b, h) do { _Pragma("unroll") for (int n = 0; n < 2; ++n) _Pragma("unroll") for (int k = 0; k < 2; ++k) dst[n][k] = *(const LAS bf16x8*)(lds + PG8_SB(b, h) + boff + n * 2048 + k * 1024); } while (0)
; #define PG8_MMA(ai, bj, At, Bt) do { __builtin_amdgcn_s_setprio(1); _Pragma("unroll") for (int m = 0; m < 4; ++m) _Pragma("unroll") for (int n = 0; n < 2; ++n) _Pragma("unroll") for (int k = 0; k < 2; ++k) \
;         acc[ai][bj][m][n] = __builtin_amdgcn_mfma_f32_16x16x32_bf16(Bt[n][k], At[m][k], acc[ai][bj][m][n], 0, 0, 0); __builtin_amdgcn_s_setprio(0); } while (0)
; #define PG8_WAIT_V(n) asm volatile("s_waitcnt vmcnt(" #n ")" ::: "memory")
; #define PG8_WAIT_L(n) asm volatile("s_waitcnt lgkmcnt(" #n ")" ::: "memory")
; #define PG8_BAR __builtin_amdgcn_s_barrier()
; #define PG8_SCHED __builtin_amdgcn_sched_barrier(0)
; template <class Epi>
; __device__ __forceinline__ void gemm_phase(LAS unsigned char* lds, const Gemm g, const StaticOrder& S_in, const Epi& E, int sw) {
;     ...
;             PG8_LDB(B0, 0, 0); PG8_SCHED; PG8_LDA(At, 0, 0); PG8_STAGE(PG8_SA(1, 1), a1 + hstepA, voffA);
;             PG8_WAIT_L(8); PG8_BAR; PG8_WAIT_L(0); PG8_MMA(0, 0, At, B0); PG8_BAR; PG8_SCHED;
;     ...
;             PG8_BAR; PG8_WAIT_L(0); PG8_MMA(0, 1, At, B1); PG8_BAR;
;             PG8_LDA(At, 1, 1); PG8_STAGE(PG8_SA(1, 0), a3, voffA);
;             PG8_BAR; PG8_WAIT_L(0); PG8_MMA(1, 0, At, B0); PG8_BAR; PG8_SCHED;
;             PG8_STAGE(PG8_SB(1, 1), b3 + hstepB, voffB);
;             PG8_WAIT_V(6); PG8_BAR; PG8_MMA(1, 1, At, B1); PG8_BAR;
	s_waitcnt lgkmcnt(0)
	s_setprio 1
	s_waitcnt lgkmcnt(0)
	v_mfma_f32_16x16x32_bf16 v[114:117], v[192:195], v[122:125], v[114:117]
	v_mfma_f32_16x16x32_bf16 v[34:37], v[200:203], v[122:125], v[34:37]
	v_mfma_f32_16x16x32_bf16 v[38:41], v[192:195], v[136:139], v[38:41]
	v_mfma_f32_16x16x32_bf16 v[42:45], v[200:203], v[136:139], v[42:45]
	v_mfma_f32_16x16x32_bf16 v[46:49], v[192:195], v[144:147], v[46:49]
	v_mfma_f32_16x16x32_bf16 v[50:53], v[200:203], v[144:147], v[50:53]
	v_mfma_f32_16x16x32_bf16 v[54:57], v[192:195], v[184:187], v[54:57]
	v_mfma_f32_16x16x32_bf16 v[58:61], v[200:203], v[184:187], v[58:61]
	v_mfma_f32_16x16x32_bf16 v[114:117], v[196:199], v[126:129], v[114:117]
	v_mfma_f32_16x16x32_bf16 v[34:37], v[204:207], v[126:129], v[34:37]
	v_mfma_f32_16x16x32_bf16 v[38:41], v[196:199], v[140:143], v[38:41]
	v_mfma_f32_16x16x32_bf16 v[42:45], v[204:207], v[140:143], v[42:45]
	v_mfma_f32_16x16x32_bf16 v[46:49], v[196:199], v[148:151], v[46:49]
	v_mfma_f32_16x16x32_bf16 v[50:53], v[204:207], v[148:151], v[50:53]
	v_mfma_f32_16x16x32_bf16 v[54:57], v[196:199], v[188:191], v[54:57]
	v_mfma_f32_16x16x32_bf16 v[58:61], v[204:207], v[188:191], v[58:61]
	s_setprio 0
	s_mov_b32 m0, s45
	v_lshl_add_u64 v[168:169], v[208:209], 0, s[58:59]
	s_barrier
	ds_read_b128 v[122:125], v174 offset:49152
	ds_read_b128 v[126:129], v174 offset:50176
	ds_read_b128 v[136:139], v174 offset:51200
	ds_read_b128 v[140:143], v174 offset:52224
	ds_read_b128 v[144:147], v174 offset:53248
	ds_read_b128 v[148:151], v174 offset:54272
	ds_read_b128 v[184:187], v174 offset:55296
	ds_read_b128 v[188:191], v174 offset:56320
	global_load_lds_dwordx4 v[168:169], off
	v_lshl_add_u64 v[168:169], v[210:211], 0, s[58:59]
	s_mov_b32 m0, s46
	s_nop 0
	global_load_lds_dwordx4 v[168:169], off
	s_barrier
	s_waitcnt lgkmcnt(0)
	s_setprio 1
	s_waitcnt lgkmcnt(0)
	v_mfma_f32_16x16x32_bf16 v[152:155], v[98:101], v[122:125], v[152:155]
	v_mfma_f32_16x16x32_bf16 v[156:159], v[106:109], v[122:125], v[156:159]
	v_mfma_f32_16x16x32_bf16 v[160:163], v[98:101], v[136:139], v[160:163]
	v_mfma_f32_16x16x32_bf16 v[164:167], v[106:109], v[136:139], v[164:167]
	v_mfma_f32_16x16x32_bf16 v[10:13], v[98:101], v[184:187], v[10:13]
	v_mfma_f32_16x16x32_bf16 v[14:17], v[106:109], v[184:187], v[14:17]
	v_mfma_f32_16x16x32_bf16 v[152:155], v[102:105], v[126:129], v[152:155]
	v_mfma_f32_16x16x32_bf16 v[156:159], v[110:113], v[126:129], v[156:159]
	v_mfma_f32_16x16x32_bf16 v[160:163], v[102:105], v[140:143], v[160:163]
	v_mfma_f32_16x16x32_bf16 v[164:167], v[110:113], v[140:143], v[164:167]
	v_mfma_f32_16x16x32_bf16 v[176:179], v[98:101], v[144:147], v[176:179]
	v_mfma_f32_16x16x32_bf16 v[180:183], v[106:109], v[144:147], v[180:183]
	v_mfma_f32_16x16x32_bf16 v[10:13], v[102:105], v[188:191], v[10:13]
	v_mfma_f32_16x16x32_bf16 v[14:17], v[110:113], v[188:191], v[14:17]
	v_mfma_f32_16x16x32_bf16 v[176:179], v[102:105], v[148:151], v[176:179]
	v_mfma_f32_16x16x32_bf16 v[180:183], v[110:113], v[148:151], v[180:183]
	s_setprio 0
	s_barrier
	s_add_u32 s54, s28, 0x10180
	s_addc_u32 s55, s29, 0
	s_add_i32 s29, s56, s38
	v_lshl_add_u64 v[98:99], s[54:55], 0, v[0:1]
	s_mov_b32 m0, s29
	s_add_i32 s28, s29, 0x2000
	global_load_lds_dwordx4 v[98:99], off
	v_lshl_add_u64 v[98:99], s[54:55], 0, v[134:135]
	s_mov_b32 m0, s28
	s_nop 0
	global_load_lds_dwordx4 v[98:99], off
	s_waitcnt vmcnt(6)
	s_barrier
	s_setprio 1
	v_mfma_f32_16x16x32_bf16 v[18:21], v[192:195], v[122:125], v[18:21]
	v_mfma_f32_16x16x32_bf16 v[22:25], v[200:203], v[122:125], v[22:25]
	v_mfma_f32_16x16x32_bf16 v[26:29], v[192:195], v[136:139], v[26:29]
	v_mfma_f32_16x16x32_bf16 v[30:33], v[200:203], v[136:139], v[30:33]
	v_mfma_f32_16x16x32_bf16 v[62:65], v[192:195], v[144:147], v[62:65]
	v_mfma_f32_16x16x32_bf16 v[98:101], v[200:203], v[144:147], v[118:121]
	v_mfma_f32_16x16x32_bf16 v[2:5], v[192:195], v[184:187], v[2:5]
	v_mfma_f32_16x16x32_bf16 v[6:9], v[200:203], v[184:187], v[6:9]
	v_mfma_f32_16x16x32_bf16 v[18:21], v[196:199], v[126:129], v[18:21]
	v_mfma_f32_16x16x32_bf16 v[22:25], v[204:207], v[126:129], v[22:25]
	v_mfma_f32_16x16x32_bf16 v[26:29], v[196:199], v[140:143], v[26:29]
	v_mfma_f32_16x16x32_bf16 v[30:33], v[204:207], v[140:143], v[30:33]
	v_mfma_f32_16x16x32_bf16 v[62:65], v[196:199], v[148:151], v[62:65]
	v_mfma_f32_16x16x32_bf16 v[98:101], v[204:207], v[148:151], v[98:101]
	v_mfma_f32_16x16x32_bf16 v[2:5], v[196:199], v[188:191], v[2:5]
	v_mfma_f32_16x16x32_bf16 v[6:9], v[204:207], v[188:191], v[6:9]
	s_setprio 0
	s_barrier
	ds_read_b128 v[102:105], v175
	ds_read_b128 v[106:109], v175 offset:1024
	ds_read_b128 v[110:113], v175 offset:2048
	ds_read_b128 v[118:121], v175 offset:3072
	s_add_u32 s26, s26, 0x80180
	s_addc_u32 s27, s27, 0
	s_mov_b32 m0, s50
	v_lshl_add_u64 v[168:169], s[26:27], 0, v[130:131]
	ds_read_b128 v[122:125], v174
	ds_read_b128 v[126:129], v174 offset:1024
	ds_read_b128 v[136:139], v174 offset:2048
	ds_read_b128 v[140:143], v174 offset:3072
	ds_read_b128 v[144:147], v174 offset:4096
	ds_read_b128 v[148:151], v174 offset:5120
	ds_read_b128 v[184:187], v174 offset:6144
	ds_read_b128 v[188:191], v174 offset:7168
	global_load_lds_dwordx4 v[168:169], off
	v_lshl_add_u64 v[168:169], s[26:27], 0, v[132:133]
	s_mov_b32 m0, s13
	s_nop 0
	global_load_lds_dwordx4 v[168:169], off
	s_waitcnt lgkmcnt(8)
	s_barrier
; #define PG8_STAGE(bufoff, gbase, voff) do { _Pragma("unroll") for (int _i = 0; _i < 2; ++_i) \
;         __builtin_amdgcn_global_load_lds((const __attribute__((address_space(1))) unsigned*)((const char*)(gbase) + (voff)[_i]), (LAS unsigned*)(lds + (bufoff) + ldsw + _i * 8192), 16, 0, 0); } while (0)
; #define PG8_LDA(dst, b, h) do { _Pragma("unroll") for (int m = 0; m < 4; ++m) _Pragma("unroll") for (int k = 0; k < 2; ++k) dst[m][k] = *(const LAS bf16x8*)(lds + PG8_SA(b, h) + aoff + m * 2048 + k * 1024); } while (0)
; #define PG8_LDB(dst, b, h) do { _Pragma("unroll") for (int n = 0; n < 2; ++n) _Pragma("unroll") for (int k = 0; k < 2; ++k) dst[n][k] = *(const LAS bf16x8*)(lds + PG8_SB(b, h) + boff + n * 2048 + k * 1024); } while (0)
; #define PG8_MMA(ai, bj, At, Bt) do { __builtin_amdgcn_s_setprio(1); _Pragma("unroll") for (int m = 0; m < 4; ++m) _Pragma("unroll") for (int n = 0; n < 2; ++n) _Pragma("unroll") for (int k = 0; k < 2; ++k) \
;         acc[ai][bj][m][n] = __builtin_amdgcn_mfma_f32_16x16x32_bf16(Bt[n][k], At[m][k], acc[ai][bj][m][n], 0, 0, 0); __builtin_amdgcn_s_setprio(0); } while (0)
; #define PG8_WAIT_V(n) asm volatile("s_waitcnt vmcnt(" #n ")" ::: "memory")
; #define PG8_WAIT_L(n) asm volatile("s_waitcnt lgkmcnt(" #n ")" ::: "memory")
; #define PG8_BAR __builtin_amdgcn_s_barrier()
; #define PG8_SCHED __builtin_amdgcn_sched_barrier(0)
; template <class Epi>
; __device__ __forceinline__ void gemm_phase(LAS unsigned char* lds, const Gemm g, const StaticOrder& S_in, const Epi& E, int sw) {
;     ...
;             PG8_WAIT_L(8); PG8_BAR; PG8_WAIT_L(0); PG8_MMA(0, 0, At, B0); PG8_BAR; PG8_SCHED;
;             PG8_LDB(B1, 0, 1); PG8_STAGE(PG8_SB(0, 0), b2, voffB);
;             PG8_BAR; PG8_WAIT_L(0); PG8_MMA(0, 1, At, B1); PG8_BAR;
;             PG8_LDA(At, 0, 1); PG8_STAGE(PG8_SA(0, 0), a2, voffA);
;             PG8_BAR; PG8_WAIT_L(0); PG8_MMA(1, 0, At, B0); PG8_BAR; PG8_SCHED;
;             PG8_STAGE(PG8_SB(0, 1), b2 + hstepB, voffB);
;             PG8_WAIT_V(6); PG8_BAR; PG8_MMA(1, 1, At, B1); PG8_BAR;
	s_waitcnt lgkmcnt(0)
	s_setprio 1
	s_waitcnt lgkmcnt(0)
	v_mfma_f32_16x16x32_bf16 v[66:69], v[102:105], v[122:125], v[66:69]
	v_mfma_f32_16x16x32_bf16 v[70:73], v[110:113], v[122:125], v[70:73]
	v_mfma_f32_16x16x32_bf16 v[74:77], v[102:105], v[136:139], v[74:77]
	v_mfma_f32_16x16x32_bf16 v[78:81], v[110:113], v[136:139], v[78:81]
	v_mfma_f32_16x16x32_bf16 v[82:85], v[102:105], v[144:147], v[82:85]
	v_mfma_f32_16x16x32_bf16 v[86:89], v[110:113], v[144:147], v[86:89]
	v_mfma_f32_16x16x32_bf16 v[90:93], v[102:105], v[184:187], v[90:93]
	v_mfma_f32_16x16x32_bf16 v[94:97], v[110:113], v[184:187], v[94:97]
	v_mfma_f32_16x16x32_bf16 v[66:69], v[106:109], v[126:129], v[66:69]
	v_mfma_f32_16x16x32_bf16 v[70:73], v[118:121], v[126:129], v[70:73]
	v_mfma_f32_16x16x32_bf16 v[74:77], v[106:109], v[140:143], v[74:77]
	v_mfma_f32_16x16x32_bf16 v[78:81], v[118:121], v[140:143], v[78:81]
	v_mfma_f32_16x16x32_bf16 v[82:85], v[106:109], v[148:151], v[82:85]
	v_mfma_f32_16x16x32_bf16 v[86:89], v[118:121], v[148:151], v[86:89]
	v_mfma_f32_16x16x32_bf16 v[90:93], v[106:109], v[188:191], v[90:93]
	v_mfma_f32_16x16x32_bf16 v[94:97], v[118:121], v[188:191], v[94:97]
	s_setprio 0
	s_barrier
	s_mov_b32 m0, s49
	v_lshl_add_u64 v[168:169], s[30:31], 0, v[0:1]
	ds_read_b128 v[192:195], v212
	ds_read_b128 v[196:199], v212 offset:1024
	ds_read_b128 v[200:203], v212 offset:2048
	ds_read_b128 v[204:207], v212 offset:3072
	global_load_lds_dwordx4 v[168:169], off
	v_lshl_add_u64 v[172:173], s[30:31], 0, v[134:135]
	s_mov_b32 m0, s17
	s_nop 0
	global_load_lds_dwordx4 v[172:173], off
	s_barrier
	s_waitcnt lgkmcnt(0)
	s_setprio 1
	s_waitcnt lgkmcnt(0)
	v_mfma_f32_16x16x32_bf16 v[50:53], v[200:203], v[144:147], v[50:53]
	v_mfma_f32_16x16x32_bf16 v[38:41], v[192:195], v[136:139], v[38:41]
	v_mfma_f32_16x16x32_bf16 v[42:45], v[200:203], v[136:139], v[42:45]
	v_mfma_f32_16x16x32_bf16 v[136:139], v[204:207], v[148:151], v[50:53]
	v_mfma_f32_16x16x32_bf16 v[50:53], v[192:195], v[184:187], v[54:57]
	v_mfma_f32_16x16x32_bf16 v[34:37], v[200:203], v[122:125], v[34:37]
	v_mfma_f32_16x16x32_bf16 v[38:41], v[196:199], v[140:143], v[38:41]
	v_mfma_f32_16x16x32_bf16 v[42:45], v[204:207], v[140:143], v[42:45]
	v_mfma_f32_16x16x32_bf16 v[46:49], v[192:195], v[144:147], v[46:49]
	v_mfma_f32_16x16x32_bf16 v[140:143], v[196:199], v[188:191], v[50:53]
	v_mfma_f32_16x16x32_bf16 v[50:53], v[200:203], v[184:187], v[58:61]
	v_mfma_f32_16x16x32_bf16 v[114:117], v[192:195], v[122:125], v[114:117]
	v_mfma_f32_16x16x32_bf16 v[34:37], v[204:207], v[126:129], v[34:37]
	v_mfma_f32_16x16x32_bf16 v[46:49], v[196:199], v[148:151], v[46:49]
	v_mfma_f32_16x16x32_bf16 v[144:147], v[204:207], v[188:191], v[50:53]
	v_mfma_f32_16x16x32_bf16 v[208:211], v[196:199], v[126:129], v[114:117]
	s_setprio 0
	s_mov_b32 m0, s23
	v_lshl_add_u64 v[240:241], s[34:35], 0, v[130:131]
	s_barrier
	ds_read_b128 v[50:53], v174 offset:16384
	ds_read_b128 v[54:57], v174 offset:17408
	ds_read_b128 v[58:61], v174 offset:18432
	ds_read_b128 v[114:117], v174 offset:19456
	ds_read_b128 v[122:125], v174 offset:20480
	ds_read_b128 v[126:129], v174 offset:21504
	ds_read_b128 v[148:151], v174 offset:22528
	ds_read_b128 v[184:187], v174 offset:23552
	global_load_lds_dwordx4 v[240:241], off
	v_lshl_add_u64 v[242:243], s[34:35], 0, v[132:133]
	s_mov_b32 m0, s25
	s_nop 0
	global_load_lds_dwordx4 v[242:243], off
	s_barrier
	s_waitcnt lgkmcnt(0)
	s_setprio 1
	s_waitcnt lgkmcnt(0)
	v_mfma_f32_16x16x32_bf16 v[152:155], v[102:105], v[50:53], v[152:155]
	v_mfma_f32_16x16x32_bf16 v[156:159], v[110:113], v[50:53], v[156:159]
	v_mfma_f32_16x16x32_bf16 v[160:163], v[102:105], v[58:61], v[160:163]
	v_mfma_f32_16x16x32_bf16 v[164:167], v[110:113], v[58:61], v[164:167]
	v_mfma_f32_16x16x32_bf16 v[10:13], v[102:105], v[148:151], v[10:13]
	v_mfma_f32_16x16x32_bf16 v[14:17], v[110:113], v[148:151], v[14:17]
	v_mfma_f32_16x16x32_bf16 v[152:155], v[106:109], v[54:57], v[152:155]
	v_mfma_f32_16x16x32_bf16 v[156:159], v[118:121], v[54:57], v[156:159]
	v_mfma_f32_16x16x32_bf16 v[160:163], v[106:109], v[114:117], v[160:163]
	v_mfma_f32_16x16x32_bf16 v[164:167], v[118:121], v[114:117], v[164:167]
	v_mfma_f32_16x16x32_bf16 v[176:179], v[102:105], v[122:125], v[176:179]
	v_mfma_f32_16x16x32_bf16 v[180:183], v[110:113], v[122:125], v[180:183]
	v_mfma_f32_16x16x32_bf16 v[10:13], v[106:109], v[184:187], v[10:13]
	v_mfma_f32_16x16x32_bf16 v[14:17], v[118:121], v[184:187], v[14:17]
	v_mfma_f32_16x16x32_bf16 v[176:179], v[106:109], v[126:129], v[176:179]
	v_mfma_f32_16x16x32_bf16 v[180:183], v[118:121], v[126:129], v[180:183]
	s_setprio 0
	s_barrier
	s_add_u32 s26, s30, 0x10000
	s_addc_u32 s27, s31, 0
	s_mov_b32 m0, s51
	v_lshl_add_u64 v[102:103], s[26:27], 0, v[0:1]
	global_load_lds_dwordx4 v[102:103], off
	v_lshl_add_u64 v[102:103], s[26:27], 0, v[134:135]
	s_mov_b32 m0, s48
	s_nop 0
	global_load_lds_dwordx4 v[102:103], off
	s_waitcnt vmcnt(6)
	s_barrier
	s_setprio 1
	v_mfma_f32_16x16x32_bf16 v[26:29], v[192:195], v[58:61], v[26:29]
	v_mfma_f32_16x16x32_bf16 v[188:191], v[196:199], v[114:117], v[26:29]
	v_mfma_f32_16x16x32_bf16 v[26:29], v[200:203], v[58:61], v[30:33]
	v_mfma_f32_16x16x32_bf16 v[18:21], v[192:195], v[50:53], v[18:21]
	v_mfma_f32_16x16x32_bf16 v[22:25], v[200:203], v[50:53], v[22:25]
	v_mfma_f32_16x16x32_bf16 v[212:215], v[204:207], v[114:117], v[26:29]
	v_mfma_f32_16x16x32_bf16 v[26:29], v[192:195], v[122:125], v[62:65]
	v_mfma_f32_16x16x32_bf16 v[2:5], v[192:195], v[148:151], v[2:5]
	v_mfma_f32_16x16x32_bf16 v[6:9], v[200:203], v[148:151], v[6:9]
	v_mfma_f32_16x16x32_bf16 v[18:21], v[196:199], v[54:57], v[18:21]
	v_mfma_f32_16x16x32_bf16 v[22:25], v[204:207], v[54:57], v[22:25]
	v_mfma_f32_16x16x32_bf16 v[62:65], v[196:199], v[126:129], v[26:29]
	v_mfma_f32_16x16x32_bf16 v[26:29], v[200:203], v[122:125], v[98:101]
	v_mfma_f32_16x16x32_bf16 v[2:5], v[196:199], v[184:187], v[2:5]
	v_mfma_f32_16x16x32_bf16 v[6:9], v[204:207], v[184:187], v[6:9]
	v_mfma_f32_16x16x32_bf16 v[216:219], v[204:207], v[126:129], v[26:29]
	s_setprio 0
	s_barrier
; #define PG8_STAGE(bufoff, gbase, voff) do { _Pragma("unroll") for (int _i = 0; _i < 2; ++_i) \
;         __builtin_amdgcn_global_load_lds((const __attribute__((address_space(1))) unsigned*)((const char*)(gbase) + (voff)[_i]), (LAS unsigned*)(lds + (bufoff) + ldsw + _i * 8192), 16, 0, 0); } while (0)
; #define PG8_LDA(dst, b, h) do { _Pragma("unroll") for (int m = 0; m < 4; ++m) _Pragma("unroll") for (int k = 0; k < 2; ++k) dst[m][k] = *(const LAS bf16x8*)(lds + PG8_SA(b, h) + aoff + m * 2048 + k * 1024); } while (0)
; #define PG8_LDB(dst, b, h) do { _Pragma("unroll") for (int n = 0; n < 2; ++n) _Pragma("unroll") for (int k = 0; k < 2; ++k) dst[n][k] = *(const LAS bf16x8*)(lds + PG8_SB(b, h) + boff + n * 2048 + k * 1024); } while (0)
; #define PG8_MMA(ai, bj, At, Bt) do { __builtin_amdgcn_s_setprio(1); _Pragma("unroll") for (int m = 0; m < 4; ++m) _Pragma("unroll") for (int n = 0; n < 2; ++n) _Pragma("unroll") for (int k = 0; k < 2; ++k) \
;         acc[ai][bj][m][n] = __builtin_amdgcn_mfma_f32_16x16x32_bf16(Bt[n][k], At[m][k], acc[ai][bj][m][n], 0, 0, 0); __builtin_amdgcn_s_setprio(0); } while (0)
; #define PG8_WAIT_V(n) asm volatile("s_waitcnt vmcnt(" #n ")" ::: "memory")
; #define PG8_WAIT_L(n) asm volatile("s_waitcnt lgkmcnt(" #n ")" ::: "memory")
; #define PG8_BAR __builtin_amdgcn_s_barrier()
; #define PG8_SCHED __builtin_amdgcn_sched_barrier(0)
; template <class Epi>
; __device__ __forceinline__ void gemm_phase(LAS unsigned char* lds, const Gemm g, const StaticOrder& S_in, const Epi& E, int sw) {
;     ...
;             PG8_LDB(B0, 1, 0); PG8_SCHED; PG8_LDA(At, 1, 0); PG8_STAGE(PG8_SA(0, 1), a2 + hstepA, voffA);
;             PG8_WAIT_L(8); PG8_BAR; PG8_WAIT_L(0); PG8_MMA(0, 0, At, B0); PG8_BAR; PG8_SCHED;
;             PG8_LDB(B1, 1, 1); PG8_STAGE(PG8_SB(1, 0), b3, voffB);
;             PG8_BAR; PG8_WAIT_L(0); PG8_MMA(0, 1, At, B1); PG8_BAR;
;             PG8_LDA(At, 1, 1); PG8_STAGE(PG8_SA(1, 0), a3, voffA);
;             PG8_BAR; PG8_WAIT_L(0); PG8_MMA(1, 0, At, B0); PG8_BAR; PG8_SCHED;
;             PG8_STAGE(PG8_SB(1, 1), b3 + hstepB, voffB);
;             PG8_WAIT_V(6); PG8_BAR; PG8_MMA(1, 1, At, B1); PG8_BAR;
	s_nop 2
	ds_read_b128 v[26:29], v220
	ds_read_b128 v[30:33], v220 offset:1024
	ds_read_b128 v[148:151], v220 offset:2048
	ds_read_b128 v[184:187], v220 offset:3072
	s_add_u32 s26, s34, 0x80000
	s_addc_u32 s27, s35, 0
	s_mov_b32 m0, s43
	v_lshl_add_u64 v[58:59], s[26:27], 0, v[130:131]
	ds_read_b128 v[50:53], v174 offset:32768
	ds_read_b128 v[54:57], v174 offset:33792
	ds_read_b128 v[98:101], v174 offset:34816
	ds_read_b128 v[102:105], v174 offset:35840
	ds_read_b128 v[110:113], v174 offset:36864
	ds_read_b128 v[192:195], v174 offset:37888
	ds_read_b128 v[196:199], v174 offset:38912
	ds_read_b128 v[200:203], v174 offset:39936
	global_load_lds_dwordx4 v[58:59], off
	v_lshl_add_u64 v[58:59], s[26:27], 0, v[132:133]
	s_mov_b32 m0, s44
	s_nop 0
	global_load_lds_dwordx4 v[58:59], off
	s_waitcnt lgkmcnt(8)
	s_barrier
	s_waitcnt lgkmcnt(0)
	s_setprio 1
	s_waitcnt lgkmcnt(0)
	v_mfma_f32_16x16x32_bf16 v[58:61], v[26:29], v[50:53], v[66:69]
	v_mfma_f32_16x16x32_bf16 v[204:207], v[30:33], v[54:57], v[58:61]
	v_mfma_f32_16x16x32_bf16 v[58:61], v[148:151], v[50:53], v[70:73]
	v_mfma_f32_16x16x32_bf16 v[220:223], v[184:187], v[54:57], v[58:61]
	v_mfma_f32_16x16x32_bf16 v[58:61], v[26:29], v[98:101], v[74:77]
	v_mfma_f32_16x16x32_bf16 v[224:227], v[30:33], v[102:105], v[58:61]
	v_mfma_f32_16x16x32_bf16 v[58:61], v[148:151], v[98:101], v[78:81]
	v_mfma_f32_16x16x32_bf16 v[126:129], v[184:187], v[102:105], v[58:61]
	v_mfma_f32_16x16x32_bf16 v[58:61], v[26:29], v[110:113], v[82:85]
	v_mfma_f32_16x16x32_bf16 v[122:125], v[30:33], v[192:195], v[58:61]
	v_mfma_f32_16x16x32_bf16 v[58:61], v[148:151], v[110:113], v[86:89]
	v_mfma_f32_16x16x32_bf16 v[118:121], v[184:187], v[192:195], v[58:61]
	v_mfma_f32_16x16x32_bf16 v[58:61], v[26:29], v[196:199], v[90:93]
	v_mfma_f32_16x16x32_bf16 v[114:117], v[30:33], v[200:203], v[58:61]
	v_mfma_f32_16x16x32_bf16 v[58:61], v[148:151], v[196:199], v[94:97]
	v_mfma_f32_16x16x32_bf16 v[106:109], v[184:187], v[200:203], v[58:61]
	s_setprio 0
	s_barrier
	s_mov_b32 m0, s53
	s_nop 3
	v_lshl_add_u64 v[58:59], v[168:169], 0, s[86:87]
	ds_read_b128 v[78:81], v232
	ds_read_b128 v[82:85], v232 offset:1024
	ds_read_b128 v[228:231], v232 offset:2048
	ds_read_b128 v[232:235], v232 offset:3072
	global_load_lds_dwordx4 v[58:59], off
	v_lshl_add_u64 v[58:59], v[172:173], 0, s[86:87]
	s_mov_b32 m0, s52
	s_nop 0
	global_load_lds_dwordx4 v[58:59], off
	s_barrier
	s_waitcnt lgkmcnt(0)
	s_setprio 1
	s_waitcnt lgkmcnt(0)
	v_mfma_f32_16x16x32_bf16 v[34:37], v[228:231], v[50:53], v[34:37]
	v_mfma_f32_16x16x32_bf16 v[66:69], v[232:235], v[54:57], v[34:37]
	v_mfma_f32_16x16x32_bf16 v[34:37], v[78:81], v[98:101], v[38:41]
	v_mfma_f32_16x16x32_bf16 v[58:61], v[78:81], v[50:53], v[208:211]
	v_mfma_f32_16x16x32_bf16 v[50:53], v[82:85], v[102:105], v[34:37]
	v_mfma_f32_16x16x32_bf16 v[34:37], v[228:231], v[98:101], v[42:45]
	v_mfma_f32_16x16x32_bf16 v[58:61], v[82:85], v[54:57], v[58:61]
	v_mfma_f32_16x16x32_bf16 v[54:57], v[232:235], v[102:105], v[34:37]
	v_mfma_f32_16x16x32_bf16 v[34:37], v[78:81], v[110:113], v[46:49]
	v_mfma_f32_16x16x32_bf16 v[42:45], v[82:85], v[192:195], v[34:37]
	v_mfma_f32_16x16x32_bf16 v[34:37], v[228:231], v[110:113], v[136:139]
	v_mfma_f32_16x16x32_bf16 v[46:49], v[232:235], v[192:195], v[34:37]
	v_mfma_f32_16x16x32_bf16 v[34:37], v[78:81], v[196:199], v[140:143]
	v_mfma_f32_16x16x32_bf16 v[38:41], v[228:231], v[196:199], v[144:147]
	v_mfma_f32_16x16x32_bf16 v[34:37], v[82:85], v[200:203], v[34:37]
	v_mfma_f32_16x16x32_bf16 v[38:41], v[232:235], v[200:203], v[38:41]
	s_setprio 0
	s_mov_b32 m0, s45
	v_lshl_add_u64 v[70:71], v[240:241], 0, s[86:87]
	s_barrier
	ds_read_b128 v[136:139], v174 offset:49152
	ds_read_b128 v[140:143], v174 offset:50176
	ds_read_b128 v[144:147], v174 offset:51200
	ds_read_b128 v[192:195], v174 offset:52224
	ds_read_b128 v[196:199], v174 offset:53248
	ds_read_b128 v[200:203], v174 offset:54272
	ds_read_b128 v[208:211], v174 offset:55296
	ds_read_b128 v[236:239], v174 offset:56320
	global_load_lds_dwordx4 v[70:71], off
	v_lshl_add_u64 v[70:71], v[242:243], 0, s[86:87]
	s_mov_b32 m0, s46
	s_nop 0
	global_load_lds_dwordx4 v[70:71], off
	s_barrier
	s_waitcnt lgkmcnt(0)
	s_setprio 1
	s_waitcnt lgkmcnt(0)
	v_mfma_f32_16x16x32_bf16 v[70:73], v[26:29], v[136:139], v[152:155]
	v_mfma_f32_16x16x32_bf16 v[110:113], v[30:33], v[140:143], v[70:73]
	v_mfma_f32_16x16x32_bf16 v[70:73], v[148:151], v[136:139], v[156:159]
	v_mfma_f32_16x16x32_bf16 v[102:105], v[184:187], v[140:143], v[70:73]
	v_mfma_f32_16x16x32_bf16 v[70:73], v[26:29], v[144:147], v[160:163]
	v_mfma_f32_16x16x32_bf16 v[98:101], v[30:33], v[192:195], v[70:73]
	v_mfma_f32_16x16x32_bf16 v[70:73], v[148:151], v[144:147], v[164:167]
	v_mfma_f32_16x16x32_bf16 v[94:97], v[184:187], v[192:195], v[70:73]
	v_mfma_f32_16x16x32_bf16 v[70:73], v[26:29], v[196:199], v[176:179]
	v_mfma_f32_16x16x32_bf16 v[10:13], v[26:29], v[208:211], v[10:13]
	v_mfma_f32_16x16x32_bf16 v[90:93], v[30:33], v[200:203], v[70:73]
	v_mfma_f32_16x16x32_bf16 v[70:73], v[148:151], v[196:199], v[180:183]
	v_mfma_f32_16x16x32_bf16 v[74:77], v[30:33], v[236:239], v[10:13]
	v_mfma_f32_16x16x32_bf16 v[10:13], v[148:151], v[208:211], v[14:17]
	v_mfma_f32_16x16x32_bf16 v[86:89], v[184:187], v[200:203], v[70:73]
	v_mfma_f32_16x16x32_bf16 v[70:73], v[184:187], v[236:239], v[10:13]
	s_setprio 0
	s_barrier
	s_add_u32 s26, s30, 0x10080
	s_addc_u32 s27, s31, 0
	s_mov_b32 m0, s29
	s_nop 0
	v_lshl_add_u64 v[10:11], s[26:27], 0, v[0:1]
	global_load_lds_dwordx4 v[10:11], off
	v_lshl_add_u64 v[10:11], s[26:27], 0, v[134:135]
	s_mov_b32 m0, s28
	s_nop 0
	global_load_lds_dwordx4 v[10:11], off
	s_waitcnt vmcnt(6)
	s_barrier
; #define LAS __attribute__((address_space(3)))
; __device__ __forceinline__ unsigned cvt_pk_bf16(float lo, float hi) { unsigned r; asm volatile("v_cvt_pk_bf16_f32 %0, %1, %2" : "=v"(r) : "v"(lo), "v"(hi)); return r; }
; __device__ __forceinline__ int ltid(int sw) { unsigned z = 0u; asm volatile("" : "+s"(sw), "+s"(z)); int t = sw * 64 + (int)__builtin_amdgcn_mbcnt_hi(~0u, __builtin_amdgcn_mbcnt_lo(~0u, z)); asm volatile("" : "+v"(t)); return t; }
; #define PG8_WAIT_V(n) asm volatile("s_waitcnt vmcnt(" #n ")" ::: "memory")
; #define PG8_BAR __builtin_amdgcn_s_barrier()
; template <class Epi>
; __device__ __forceinline__ void gemm_phase(LAS unsigned char* lds, const Gemm g, const StaticOrder& S_in, const Epi& E, int sw) {
;     ...
;             PG8_WAIT_V(6); PG8_BAR; PG8_MMA(1, 1, At, B1); PG8_BAR;
;     __device__ __forceinline__ void operator()(AccMut acc, const Unit& u, int sw) const {
;         const int tid_ = ltid(sw), lane_ = tid_ & 63, wr = sw >> 2, wc = sw & 3, fr = lane_ & 15, fq = lane_ >> 4;
;         const int row0 = u.pm * BM + wr * 64 + fr, c0 = u.pn * 128 + wc * 32 + 8 * fq;
;         u32x4 xnext = *(const u32x4*)(XC + (size_t)row0 * E + c0);
;         { f32x4 ns[2];
; #pragma unroll
;           for (int n = 0; n < 2; ++n) ns[n] = *(const LAS f32x4*)(nsp + c0 + 4 * n);
; #pragma unroll
;           for (int ai = 0; ai < 2; ++ai)
; #pragma unroll
;             for (int m = 0; m < 4; ++m) {
; #pragma unroll
;                 for (int n = 0; n < 2; ++n)
; #pragma unroll
;                     for (int jp = 0; jp < 2; ++jp) {
;                         const f32x2 z = (f32x2){acc[ai][0][m][n][2 * jp], acc[ai][0][m][n][2 * jp + 1]} * (-1.44269504f);
;                         f32x2 e; e.x = __builtin_amdgcn_exp2f(z.x); e.y = __builtin_amdgcn_exp2f(z.y); e = e + 1.0f;
;                         f32x2 r; r.x = __builtin_amdgcn_rcpf(e.x); r.y = __builtin_amdgcn_rcpf(e.y);
;                         r = r * (f32x2){ns[n][2 * jp], ns[n][2 * jp + 1]};
;                         acc[ai][0][m][n][2 * jp] = r.x; acc[ai][0][m][n][2 * jp + 1] = r.y; }
;                 const f32x4 l0 = acc[ai][0][m][0], l1 = acc[ai][0][m][1];
;                 u32x4 w; w.x = cvt_pk_bf16(l0[0], l0[1]); w.y = cvt_pk_bf16(l0[2], l0[3]); w.z = cvt_pk_bf16(l1[0], l1[1]); w.w = cvt_pk_bf16(l1[2], l1[3]);
;                 *(u32x4*)(LA + (size_t)(row0 + ai * HALF + m * 16) * E + c0) = w; } }
	s_setprio 1
	v_mfma_f32_16x16x32_bf16 v[10:13], v[78:81], v[136:139], v[18:21]
	v_mfma_f32_16x16x32_bf16 v[26:29], v[82:85], v[140:143], v[10:13]
	v_mfma_f32_16x16x32_bf16 v[10:13], v[228:231], v[136:139], v[22:25]
	v_mfma_f32_16x16x32_bf16 v[30:33], v[232:235], v[140:143], v[10:13]
	v_mfma_f32_16x16x32_bf16 v[10:13], v[78:81], v[144:147], v[188:191]
	v_mfma_f32_16x16x32_bf16 v[18:21], v[82:85], v[192:195], v[10:13]
	v_mfma_f32_16x16x32_bf16 v[10:13], v[228:231], v[144:147], v[212:215]
	v_mfma_f32_16x16x32_bf16 v[22:25], v[232:235], v[192:195], v[10:13]
	v_mfma_f32_16x16x32_bf16 v[10:13], v[78:81], v[196:199], v[62:65]
	v_mfma_f32_16x16x32_bf16 v[14:17], v[228:231], v[196:199], v[216:219]
	v_mfma_f32_16x16x32_bf16 v[2:5], v[78:81], v[208:211], v[2:5]
	v_mfma_f32_16x16x32_bf16 v[6:9], v[228:231], v[208:211], v[6:9]
	v_mfma_f32_16x16x32_bf16 v[10:13], v[82:85], v[200:203], v[10:13]
	v_mfma_f32_16x16x32_bf16 v[14:17], v[232:235], v[200:203], v[14:17]
	v_mfma_f32_16x16x32_bf16 v[2:5], v[82:85], v[236:239], v[2:5]
	v_mfma_f32_16x16x32_bf16 v[6:9], v[232:235], v[236:239], v[6:9]
	s_setprio 0
	s_barrier
	s_mov_b32 s13, s75
	s_mov_b32 s17, s81
	v_pk_mul_f32 v[144:145], v[220:221], s[74:75] op_sel_hi:[1,0]
	v_mbcnt_lo_u32_b32 v62, -1, s17
	v_mbcnt_hi_u32_b32 v62, -1, v62
	v_lshl_add_u32 v62, s13, 6, v62
	s_lshl_b32 s13, s24, 8
	s_add_i32 s13, s13, s3
	v_and_or_b32 v172, v62, 15, s13
	s_lshl_b32 s13, s22, 7
	v_lshrrev_b32_e32 v62, 1, v62
	v_and_or_b32 v62, v62, 24, s13
	v_or_b32_e32 v136, s85, v62
	v_ashrrev_i32_e32 v173, 31, v172
	v_pk_mul_f32 v[140:141], v[204:205], s[74:75] op_sel_hi:[1,0]
	v_pk_mul_f32 v[142:143], v[206:207], s[74:75] op_sel_hi:[1,0]
	v_exp_f32_e32 v144, v144
	v_exp_f32_e32 v145, v145
	v_lshlrev_b64 v[152:153], 12, v[172:173]
	v_ashrrev_i32_e32 v137, 31, v136
	v_exp_f32_e32 v140, v140
	v_exp_f32_e32 v141, v141
	v_exp_f32_e32 v142, v142
	v_exp_f32_e32 v143, v143
	v_pk_mul_f32 v[146:147], v[222:223], s[74:75] op_sel_hi:[1,0]
	v_lshl_add_u64 v[62:63], s[6:7], 0, v[152:153]
	v_lshlrev_b64 v[138:139], 1, v[136:137]
	v_lshl_add_u32 v78, v136, 2, 0
	v_exp_f32_e32 v146, v146
	v_exp_f32_e32 v147, v147
	v_lshl_add_u64 v[62:63], v[62:63], 0, v[138:139]
	v_add_u32_e32 v78, 0x24400, v78
	global_load_dwordx4 v[62:65], v[62:63], off
	ds_read_b128 v[82:85], v78
	ds_read_b128 v[78:81], v78 offset:16
	v_pk_add_f32 v[144:145], v[144:145], 1.0 op_sel_hi:[1,0]
	v_pk_add_f32 v[140:141], v[140:141], 1.0 op_sel_hi:[1,0]
	v_pk_add_f32 v[142:143], v[142:143], 1.0 op_sel_hi:[1,0]
	v_rcp_f32_e32 v144, v144
	v_rcp_f32_e32 v145, v145
	v_rcp_f32_e32 v140, v140
	v_rcp_f32_e32 v141, v141
	v_rcp_f32_e32 v142, v142
	v_rcp_f32_e32 v143, v143
	v_pk_add_f32 v[146:147], v[146:147], 1.0 op_sel_hi:[1,0]
	s_waitcnt lgkmcnt(0)
	v_pk_mul_f32 v[164:165], v[144:145], v[78:79]
	v_rcp_f32_e32 v146, v146
	v_rcp_f32_e32 v147, v147
	v_lshl_add_u64 v[144:145], s[8:9], 0, v[152:153]
	v_pk_mul_f32 v[168:169], v[140:141], v[82:83]
	v_pk_mul_f32 v[166:167], v[142:143], v[84:85]
	v_cvt_pk_bf16_f32 v140, v168, v169
	v_lshl_add_u64 v[144:145], v[144:145], 0, v[138:139]
	v_cvt_pk_bf16_f32 v141, v166, v167
	v_pk_mul_f32 v[162:163], v[146:147], v[80:81]
	v_cvt_pk_bf16_f32 v142, v164, v165
	v_pk_mul_f32 v[122:123], v[122:123], s[74:75] op_sel_hi:[1,0]
	v_cvt_pk_bf16_f32 v143, v162, v163
	global_store_dwordx4 v[144:145], v[140:143], off
	v_pk_mul_f32 v[126:127], v[126:127], s[74:75] op_sel_hi:[1,0]
	v_pk_mul_f32 v[128:129], v[128:129], s[74:75] op_sel_hi:[1,0]
	v_pk_mul_f32 v[140:141], v[224:225], s[74:75] op_sel_hi:[1,0]
	v_pk_mul_f32 v[142:143], v[226:227], s[74:75] op_sel_hi:[1,0]
	v_exp_f32_e32 v140, v140
	v_exp_f32_e32 v141, v141
	v_exp_f32_e32 v122, v122
	v_exp_f32_e32 v123, v123
	v_pk_mul_f32 v[114:115], v[114:115], s[74:75] op_sel_hi:[1,0]
	v_pk_add_f32 v[140:141], v[140:141], 1.0 op_sel_hi:[1,0]
	v_exp_f32_e32 v142, v142
	v_exp_f32_e32 v143, v143
	v_rcp_f32_e32 v140, v140
	v_rcp_f32_e32 v141, v141
	v_exp_f32_e32 v126, v126
	v_exp_f32_e32 v127, v127
	v_exp_f32_e32 v128, v128
	v_exp_f32_e32 v129, v129
	v_exp_f32_e32 v114, v114
	v_exp_f32_e32 v115, v115
	v_pk_mul_f32 v[116:117], v[116:117], s[74:75] op_sel_hi:[1,0]
	v_pk_mul_f32 v[124:125], v[124:125], s[74:75] op_sel_hi:[1,0]
	v_exp_f32_e32 v116, v116
	v_exp_f32_e32 v117, v117
	v_pk_add_f32 v[122:123], v[122:123], 1.0 op_sel_hi:[1,0]
	v_pk_mul_f32 v[118:119], v[118:119], s[74:75] op_sel_hi:[1,0]
	v_pk_mul_f32 v[120:121], v[120:121], s[74:75] op_sel_hi:[1,0]
	v_pk_mul_f32 v[106:107], v[106:107], s[74:75] op_sel_hi:[1,0]
	v_pk_mul_f32 v[108:109], v[108:109], s[74:75] op_sel_hi:[1,0]
	v_pk_add_f32 v[142:143], v[142:143], 1.0 op_sel_hi:[1,0]
	v_pk_add_f32 v[126:127], v[126:127], 1.0 op_sel_hi:[1,0]
	v_pk_add_f32 v[128:129], v[128:129], 1.0 op_sel_hi:[1,0]
	v_pk_mul_f32 v[160:161], v[140:141], v[82:83]
	v_or_b32_e32 v140, 16, v172
	v_exp_f32_e32 v124, v124
	v_exp_f32_e32 v125, v125
	v_rcp_f32_e32 v122, v122
	v_rcp_f32_e32 v123, v123
	v_exp_f32_e32 v118, v118
	v_exp_f32_e32 v119, v119
	v_exp_f32_e32 v120, v120
	v_exp_f32_e32 v121, v121
	v_pk_add_f32 v[114:115], v[114:115], 1.0 op_sel_hi:[1,0]
	v_exp_f32_e32 v106, v106
	v_exp_f32_e32 v107, v107
	v_exp_f32_e32 v108, v108
	v_exp_f32_e32 v109, v109
	v_rcp_f32_e32 v142, v142
	v_rcp_f32_e32 v143, v143
	v_rcp_f32_e32 v126, v126
	v_rcp_f32_e32 v127, v127
	v_rcp_f32_e32 v128, v128
	v_rcp_f32_e32 v129, v129
	v_ashrrev_i32_e32 v141, 31, v140
	v_rcp_f32_e32 v114, v114
	v_rcp_f32_e32 v115, v115
	v_lshlrev_b64 v[146:147], 12, v[140:141]
	v_pk_add_f32 v[116:117], v[116:117], 1.0 op_sel_hi:[1,0]
	v_lshl_add_u64 v[140:141], s[8:9], 0, v[146:147]
	v_rcp_f32_e32 v116, v116
	v_rcp_f32_e32 v117, v117
; __device__ __forceinline__ unsigned cvt_pk_bf16(float lo, float hi) { unsigned r; asm volatile("v_cvt_pk_bf16_f32 %0, %1, %2" : "=v"(r) : "v"(lo), "v"(hi)); return r; }
;     __device__ __forceinline__ void operator()(AccMut acc, const Unit& u, int sw) const {
;     ...
;           for (int ai = 0; ai < 2; ++ai)
; #pragma unroll
;             for (int m = 0; m < 4; ++m) {
; #pragma unroll
;                 for (int n = 0; n < 2; ++n)
; #pragma unroll
;                     for (int jp = 0; jp < 2; ++jp) {
;                         const f32x2 z = (f32x2){acc[ai][0][m][n][2 * jp], acc[ai][0][m][n][2 * jp + 1]} * (-1.44269504f);
;                         f32x2 e; e.x = __builtin_amdgcn_exp2f(z.x); e.y = __builtin_amdgcn_exp2f(z.y); e = e + 1.0f;
;                         f32x2 r; r.x = __builtin_amdgcn_rcpf(e.x); r.y = __builtin_amdgcn_rcpf(e.y);
;                         r = r * (f32x2){ns[n][2 * jp], ns[n][2 * jp + 1]};
;                         acc[ai][0][m][n][2 * jp] = r.x; acc[ai][0][m][n][2 * jp + 1] = r.y; }
;                 const f32x4 l0 = acc[ai][0][m][0], l1 = acc[ai][0][m][1];
;                 u32x4 w; w.x = cvt_pk_bf16(l0[0], l0[1]); w.y = cvt_pk_bf16(l0[2], l0[3]); w.z = cvt_pk_bf16(l1[0], l1[1]); w.w = cvt_pk_bf16(l1[2], l1[3]);
;                 *(u32x4*)(LA + (size_t)(row0 + ai * HALF + m * 16) * E + c0) = w; } }
	v_lshl_add_u64 v[140:141], v[140:141], 0, v[138:139]
	v_pk_add_f32 v[124:125], v[124:125], 1.0 op_sel_hi:[1,0]
	v_pk_add_f32 v[118:119], v[118:119], 1.0 op_sel_hi:[1,0]
	v_pk_add_f32 v[120:121], v[120:121], 1.0 op_sel_hi:[1,0]
	v_pk_mul_f32 v[150:151], v[122:123], v[82:83]
	v_or_b32_e32 v122, 32, v172
	v_pk_add_f32 v[106:107], v[106:107], 1.0 op_sel_hi:[1,0]
	v_pk_add_f32 v[108:109], v[108:109], 1.0 op_sel_hi:[1,0]
	v_pk_mul_f32 v[158:159], v[142:143], v[84:85]
	v_pk_mul_f32 v[156:157], v[126:127], v[78:79]
	v_pk_mul_f32 v[154:155], v[128:129], v[80:81]
	v_cvt_pk_bf16_f32 v126, v160, v161
	v_cvt_pk_bf16_f32 v127, v158, v159
	v_cvt_pk_bf16_f32 v128, v156, v157
	v_rcp_f32_e32 v124, v124
	v_cvt_pk_bf16_f32 v129, v154, v155
	global_store_dwordx4 v[140:141], v[126:129], off
	v_rcp_f32_e32 v125, v125
	v_rcp_f32_e32 v118, v118
	v_rcp_f32_e32 v119, v119
	v_rcp_f32_e32 v120, v120
	v_rcp_f32_e32 v121, v121
	v_ashrrev_i32_e32 v123, 31, v122
	v_rcp_f32_e32 v106, v106
	v_rcp_f32_e32 v107, v107
	v_rcp_f32_e32 v108, v108
	v_rcp_f32_e32 v109, v109
	v_pk_mul_f32 v[140:141], v[114:115], v[82:83]
	v_or_b32_e32 v114, 48, v172
	v_lshlrev_b64 v[126:127], 12, v[122:123]
	v_ashrrev_i32_e32 v115, 31, v114
	v_lshl_add_u64 v[122:123], s[8:9], 0, v[126:127]
	v_pk_mul_f32 v[128:129], v[116:117], v[84:85]
	v_lshlrev_b64 v[116:117], 12, v[114:115]
	v_pk_mul_f32 v[104:105], v[104:105], s[74:75] op_sel_hi:[1,0]
	v_lshl_add_u64 v[122:123], v[122:123], 0, v[138:139]
	v_lshl_add_u64 v[114:115], s[8:9], 0, v[116:117]
	v_pk_mul_f32 v[102:103], v[102:103], s[74:75] op_sel_hi:[1,0]
	v_exp_f32_e32 v104, v104
	v_exp_f32_e32 v105, v105
	v_pk_mul_f32 v[148:149], v[124:125], v[84:85]
	v_pk_mul_f32 v[144:145], v[118:119], v[78:79]
	v_pk_mul_f32 v[142:143], v[120:121], v[80:81]
	v_cvt_pk_bf16_f32 v118, v150, v151
	v_cvt_pk_bf16_f32 v119, v148, v149
	v_cvt_pk_bf16_f32 v120, v144, v145
	v_pk_mul_f32 v[124:125], v[106:107], v[78:79]
	v_cvt_pk_bf16_f32 v121, v142, v143
	global_store_dwordx4 v[122:123], v[118:121], off
	v_pk_mul_f32 v[122:123], v[108:109], v[80:81]
	v_cvt_pk_bf16_f32 v106, v140, v141
	v_cvt_pk_bf16_f32 v107, v128, v129
	v_cvt_pk_bf16_f32 v108, v124, v125
	v_lshl_add_u64 v[114:115], v[114:115], 0, v[138:139]
	v_cvt_pk_bf16_f32 v109, v122, v123
	v_exp_f32_e32 v102, v102
	v_exp_f32_e32 v103, v103
	global_store_dwordx4 v[114:115], v[106:109], off
	v_pk_mul_f32 v[94:95], v[94:95], s[74:75] op_sel_hi:[1,0]
	v_pk_add_f32 v[104:105], v[104:105], 1.0 op_sel_hi:[1,0]
	v_pk_mul_f32 v[108:109], v[110:111], s[74:75] op_sel_hi:[1,0]
	v_pk_mul_f32 v[110:111], v[112:113], s[74:75] op_sel_hi:[1,0]
	v_exp_f32_e32 v108, v108
	v_exp_f32_e32 v109, v109
	v_exp_f32_e32 v110, v110
	v_exp_f32_e32 v111, v111
	v_exp_f32_e32 v94, v94
	v_exp_f32_e32 v95, v95
	v_pk_mul_f32 v[98:99], v[98:99], s[74:75] op_sel_hi:[1,0]
	v_pk_mul_f32 v[100:101], v[100:101], s[74:75] op_sel_hi:[1,0]
	v_pk_mul_f32 v[96:97], v[96:97], s[74:75] op_sel_hi:[1,0]
	v_pk_add_f32 v[102:103], v[102:103], 1.0 op_sel_hi:[1,0]
	v_rcp_f32_e32 v104, v104
	v_rcp_f32_e32 v105, v105
	v_exp_f32_e32 v98, v98
	v_exp_f32_e32 v99, v99
	v_exp_f32_e32 v100, v100
	v_exp_f32_e32 v101, v101
	v_exp_f32_e32 v96, v96
	v_exp_f32_e32 v97, v97
	v_pk_mul_f32 v[92:93], v[92:93], s[74:75] op_sel_hi:[1,0]
	v_pk_mul_f32 v[86:87], v[86:87], s[74:75] op_sel_hi:[1,0]
	v_rcp_f32_e32 v102, v102
	v_rcp_f32_e32 v103, v103
	v_pk_mul_f32 v[90:91], v[90:91], s[74:75] op_sel_hi:[1,0]
	v_exp_f32_e32 v92, v92
	v_exp_f32_e32 v93, v93
	v_exp_f32_e32 v86, v86
	v_exp_f32_e32 v87, v87
	v_pk_mul_f32 v[88:89], v[88:89], s[74:75] op_sel_hi:[1,0]
	v_add_u32_e32 v106, 0x80, v172
	v_pk_add_f32 v[108:109], v[108:109], 1.0 op_sel_hi:[1,0]
	v_pk_add_f32 v[110:111], v[110:111], 1.0 op_sel_hi:[1,0]
	v_pk_add_f32 v[94:95], v[94:95], 1.0 op_sel_hi:[1,0]
	v_exp_f32_e32 v90, v90
	v_exp_f32_e32 v91, v91
	v_exp_f32_e32 v88, v88
	v_exp_f32_e32 v89, v89
	v_rcp_f32_e32 v108, v108
	v_rcp_f32_e32 v109, v109
	v_rcp_f32_e32 v110, v110
	v_rcp_f32_e32 v111, v111
	v_ashrrev_i32_e32 v107, 31, v106
	v_rcp_f32_e32 v94, v94
	v_rcp_f32_e32 v95, v95
	v_pk_mul_f32 v[74:75], v[74:75], s[74:75] op_sel_hi:[1,0]
	v_pk_mul_f32 v[112:113], v[104:105], v[80:81]
	v_lshlrev_b64 v[104:105], 12, v[106:107]
;     __device__ __forceinline__ void operator()(AccMut acc, const Unit& u, int sw) const {
;     ...
;                         const f32x2 z = (f32x2){acc[ai][0][m][n][2 * jp], acc[ai][0][m][n][2 * jp + 1]} * (-1.44269504f);
;                         f32x2 e; e.x = __builtin_amdgcn_exp2f(z.x); e.y = __builtin_amdgcn_exp2f(z.y); e = e + 1.0f;
;                         f32x2 r; r.x = __builtin_amdgcn_rcpf(e.x); r.y = __builtin_amdgcn_rcpf(e.y);
;                         r = r * (f32x2){ns[n][2 * jp], ns[n][2 * jp + 1]};
;                         acc[ai][0][m][n][2 * jp] = r.x; acc[ai][0][m][n][2 * jp + 1] = r.y; }
;                 const f32x4 l0 = acc[ai][0][m][0], l1 = acc[ai][0][m][1];
;                 u32x4 w; w.x = cvt_pk_bf16(l0[0], l0[1]); w.y = cvt_pk_bf16(l0[2], l0[3]); w.z = cvt_pk_bf16(l1[0], l1[1]); w.w = cvt_pk_bf16(l1[2], l1[3]);
;                 *(u32x4*)(LA + (size_t)(row0 + ai * HALF + m * 16) * E + c0) = w; } }
; #pragma unroll
;         for (int ai = 0; ai < 2; ++ai)
; #pragma unroll
;             for (int m = 0; m < 4; ++m) { const size_t off = (size_t)(row0 + ai * HALF + m * 16) * E + c0;
;                 const u32x4 xw = xnext;
;                 if (ai * 4 + m < 7) { const int ai2 = (ai * 4 + m + 1) >> 2, m2 = (ai * 4 + m + 1) & 3; xnext = *(const u32x4*)(XC + (size_t)(row0 + ai2 * HALF + m2 * 16) * E + c0); }
;                 float bt[8];
; #pragma unroll
;                 for (int n = 0; n < 2; ++n)
; #pragma unroll
;                     for (int jp = 0; jp < 2; ++jp) {
;                         const f32x2 z = (f32x2){acc[ai][1][m][n][2 * jp], acc[ai][1][m][n][2 * jp + 1]} * (-1.44269504f);
;                         f32x2 e; e.x = __builtin_amdgcn_exp2f(z.x); e.y = __builtin_amdgcn_exp2f(z.y); e = e + 1.0f;
;                         f32x2 ig; ig.x = __builtin_amdgcn_rcpf(e.x); ig.y = __builtin_amdgcn_rcpf(e.y);
;                         const f32x2 x2 = (f32x2){acc[ai][0][m][n][2 * jp], acc[ai][0][m][n][2 * jp + 1]} * 2.0f;
;                         f32x2 ser = x2 * (1.0f / 120.0f) + (1.0f / 24.0f); ser = ser * x2 + (1.0f / 6.0f); ser = ser * x2 + 0.5f; ser = ser * x2 + 1.0f; ser = ser * (-x2);
;                         f32x2 em = ser;
;                         if (__builtin_expect(__builtin_amdgcn_ballot_w64(x2.x <= -0.25f || x2.y <= -0.25f) != 0ull, 0)) {
	v_pk_add_f32 v[98:99], v[98:99], 1.0 op_sel_hi:[1,0]
	v_pk_add_f32 v[100:101], v[100:101], 1.0 op_sel_hi:[1,0]
	v_pk_add_f32 v[96:97], v[96:97], 1.0 op_sel_hi:[1,0]
	v_exp_f32_e32 v74, v74
	v_exp_f32_e32 v75, v75
	v_pk_mul_f32 v[76:77], v[76:77], s[74:75] op_sel_hi:[1,0]
	v_pk_mul_f32 v[72:73], v[72:73], s[74:75] op_sel_hi:[1,0]
	v_pk_mul_f32 v[114:115], v[102:103], v[78:79]
	v_lshl_add_u64 v[102:103], s[8:9], 0, v[104:105]
	v_rcp_f32_e32 v98, v98
	v_rcp_f32_e32 v99, v99
	v_rcp_f32_e32 v100, v100
	v_rcp_f32_e32 v101, v101
	v_rcp_f32_e32 v96, v96
	v_rcp_f32_e32 v97, v97
	v_pk_add_f32 v[92:93], v[92:93], 1.0 op_sel_hi:[1,0]
	v_pk_add_f32 v[86:87], v[86:87], 1.0 op_sel_hi:[1,0]
	v_exp_f32_e32 v76, v76
	v_exp_f32_e32 v77, v77
	v_pk_mul_f32 v[70:71], v[70:71], s[74:75] op_sel_hi:[1,0]
	v_exp_f32_e32 v72, v72
	v_exp_f32_e32 v73, v73
	v_lshl_add_u64 v[102:103], v[102:103], 0, v[138:139]
	s_mov_b64 s[26:27], 0x90000
	v_pk_add_f32 v[90:91], v[90:91], 1.0 op_sel_hi:[1,0]
	v_rcp_f32_e32 v92, v92
	v_rcp_f32_e32 v93, v93
	v_rcp_f32_e32 v86, v86
	v_rcp_f32_e32 v87, v87
	v_pk_add_f32 v[88:89], v[88:89], 1.0 op_sel_hi:[1,0]
	v_exp_f32_e32 v70, v70
	v_exp_f32_e32 v71, v71
	v_pk_mul_f32 v[120:121], v[108:109], v[82:83]
	v_pk_mul_f32 v[118:119], v[110:111], v[84:85]
	v_cvt_pk_bf16_f32 v108, v120, v121
	v_rcp_f32_e32 v90, v90
	v_cvt_pk_bf16_f32 v109, v118, v119
	v_cvt_pk_bf16_f32 v110, v114, v115
	v_cvt_pk_bf16_f32 v111, v112, v113
	global_store_dwordx4 v[102:103], v[108:111], off
	v_pk_mul_f32 v[102:103], v[94:95], v[78:79]
	v_lshl_add_u64 v[94:95], v[152:153], 0, s[26:27]
	v_rcp_f32_e32 v91, v91
	v_rcp_f32_e32 v88, v88
	v_rcp_f32_e32 v89, v89
	v_lshl_add_u64 v[172:173], s[8:9], 0, v[94:95]
	v_pk_add_f32 v[74:75], v[74:75], 1.0 op_sel_hi:[1,0]
	v_pk_mul_f32 v[110:111], v[98:99], v[82:83]
	v_pk_mul_f32 v[108:109], v[100:101], v[84:85]
	v_pk_mul_f32 v[100:101], v[96:97], v[80:81]
	v_cvt_pk_bf16_f32 v96, v110, v111
	v_cvt_pk_bf16_f32 v97, v108, v109
	v_lshl_add_u64 v[172:173], v[172:173], 0, v[138:139]
	s_mov_b64 s[26:27], 0xa0000
	v_rcp_f32_e32 v74, v74
	v_rcp_f32_e32 v75, v75
	v_pk_add_f32 v[76:77], v[76:77], 1.0 op_sel_hi:[1,0]
	v_pk_add_f32 v[72:73], v[72:73], 1.0 op_sel_hi:[1,0]
	v_cvt_pk_bf16_f32 v98, v102, v103
	v_cvt_pk_bf16_f32 v99, v100, v101
	global_store_dwordx4 v[172:173], v[96:99], off
	v_rcp_f32_e32 v76, v76
	v_rcp_f32_e32 v77, v77
	v_pk_mul_f32 v[96:97], v[92:93], v[84:85]
	v_pk_mul_f32 v[92:93], v[86:87], v[78:79]
	v_lshl_add_u64 v[86:87], v[152:153], 0, s[26:27]
	v_pk_add_f32 v[70:71], v[70:71], 1.0 op_sel_hi:[1,0]
	v_rcp_f32_e32 v72, v72
	v_rcp_f32_e32 v73, v73
	v_pk_mul_f32 v[98:99], v[90:91], v[82:83]
	v_pk_mul_f32 v[90:91], v[88:89], v[80:81]
	v_lshl_add_u64 v[88:89], s[8:9], 0, v[86:87]
	v_rcp_f32_e32 v70, v70
	v_rcp_f32_e32 v71, v71
	v_lshl_add_u64 v[88:89], v[88:89], 0, v[138:139]
	s_mov_b64 s[26:27], 0xb0000
	v_cvt_pk_bf16_f32 v176, v98, v99
	v_cvt_pk_bf16_f32 v177, v96, v97
	v_cvt_pk_bf16_f32 v178, v92, v93
	v_cvt_pk_bf16_f32 v179, v90, v91
	global_store_dwordx4 v[88:89], v[176:179], off
	v_pk_mul_f32 v[88:89], v[74:75], v[82:83]
	v_lshl_add_u64 v[74:75], v[152:153], 0, s[26:27]
	v_pk_mul_f32 v[82:83], v[76:77], v[84:85]
	v_pk_mul_f32 v[76:77], v[72:73], v[80:81]
	v_lshl_add_u64 v[80:81], s[8:9], 0, v[74:75]
	v_pk_mul_f32 v[78:79], v[70:71], v[78:79]
	v_cvt_pk_bf16_f32 v70, v88, v89
	v_cvt_pk_bf16_f32 v71, v82, v83
	v_lshl_add_u64 v[80:81], v[80:81], 0, v[138:139]
	v_cvt_pk_bf16_f32 v72, v78, v79
	v_cvt_pk_bf16_f32 v73, v76, v77
	global_store_dwordx4 v[80:81], v[70:73], off
	v_pk_add_f32 v[84:85], v[168:169], v[168:169]
	s_mov_b32 s22, 0x3e2aaaab
	v_lshl_add_u64 v[70:71], s[6:7], 0, v[146:147]
	v_lshl_add_u64 v[70:71], v[70:71], 0, v[138:139]
	global_load_dwordx4 v[70:73], v[70:71], off
	v_pk_fma_f32 v[80:81], v[84:85], s[2:3], v[170:171] op_sel_hi:[1,0,0]
	v_min_f32_e32 v107, v84, v85
	v_pk_fma_f32 v[80:81], v[84:85], v[80:81], s[22:23] op_sel_hi:[1,1,0]
	v_cmp_ge_f32_e32 vcc, s33, v107
	v_pk_fma_f32 v[80:81], v[84:85], v[80:81], 0.5 op_sel_hi:[1,1,0]
	s_nop 0
	v_pk_fma_f32 v[80:81], v[84:85], v[80:81], 1.0 op_sel_hi:[1,1,0]
	s_nop 0
	v_pk_mul_f32 v[80:81], v[80:81], v[84:85] neg_lo:[0,1] neg_hi:[0,1]
	s_cbranch_vccnz .LBB0_462
